# NSA K/V LDS tile row pitch 144B->160B (bank-conflict-free ds_read_b128 per gfx950 lane groups), on top of v19
# speedup vs baseline: 1.0056x; 1.0029x over previous
; #define LAS __attribute__((address_space(3)))
; __device__ __forceinline__ int fresh_tid() { int t = threadIdx.x; asm volatile("" : "+v"(t)); return t; }
; template <int MODE> ...
;     float Bl[16];
; #pragma unroll
;     for (int tau = 0; tau < 4; ++tau)
; #pragma unroll
;         for (int r = 0; r < 4; ++r) Bl[tau * 4 + r] = sl2 * (float)((MODE <= 1 ? 16 : 1) * (32 * (tau >> 1) + 8 * (lane >> 4) + 4 * (tau & 1) + r));
;     const int srow = tid >> 3, sch = (tid & 7) * 8;
;     const int krow = 16 * (2 * (srow >> 5) + ((srow >> 2) & 1)) + 4 * ((srow >> 3) & 3) + (srow & 3);
;     const bool selt[2] = {true, true};
;     v4u skA, svA;
; __device__ __forceinline__ void ph_nsa(LAS unsigned char* lds) {
;     ...
;     const int tid = fresh_tid();
;     const int G = gridDim.x, bx = blockIdx.x;
;     const bool xm = (G & 7) == 0;
;     const int nW = xm ? (G >> 3) : G, w0 = xm ? (bx >> 3) : bx, total = xm ? SEQ / 64 : 8 * (SEQ / 64);
; #pragma unroll 1
;     for (int u = w0, it = 0; u < total; u += nW, ++it) { const int bgx = xm ? ((bx + it) & 7) : u / (SEQ / 64), t64 = xm ? u : u % (SEQ / 64); nsa_block(lds, bgx >> 2, bgx & 3, t64 * 64, tid); }
.LBB0_893:
	s_cmp_lt_i32 s70, 6
	s_cselect_b64 s[4:5], -1, 0
	s_cmp_gt_i32 s71, 5
	s_cselect_b64 s[6:7], -1, 0
	s_and_b64 s[4:5], s[4:5], s[6:7]
	s_andn2_b64 vcc, exec, s[4:5]
	s_cbranch_vccnz .LBB0_1120
	v_mov_b32_e32 v197, v196
	s_waitcnt lgkmcnt(0)
	s_load_dword s3, s[0:1], 0xb8
	s_add_u32 s4, s0, 0xb8
	s_addc_u32 s5, s1, 0
	s_mov_b32 s21, 0
	v_writelane_b32 v255, s72, 0
	s_waitcnt lgkmcnt(0)
	s_and_b32 s3, s3, 7
	s_cmp_lg_u32 s3, 0
	s_cselect_b64 s[24:25], -1, 0
	s_ashr_i32 s6, s2, 3
	v_writelane_b32 v255, s73, 1
	s_cmp_eq_u32 s3, 0
	v_writelane_b32 v255, s4, 2
	s_cselect_b64 s[26:27], -1, 0
	s_movk_i32 s3, 0x100
	v_writelane_b32 v255, s5, 3
	s_and_b64 s[4:5], s[26:27], exec
	s_cselect_b32 s33, s6, s2
	s_cselect_b32 s76, s3, 0x800
	s_cmp_ge_i32 s33, s76
	s_cbranch_scc1 .LBB0_1066
	s_load_dword s6, s[0:1], 0xb8
	v_ashrrev_i32_e32 v2, 7, v197
	v_bfe_u32 v3, v197, 5, 1
	v_ashrrev_i32_e32 v88, 3, v197
	v_lshlrev_b32_e32 v0, 3, v197
	s_waitcnt lgkmcnt(0)
	s_ashr_i32 s3, s6, 3
	s_and_b64 s[4:5], s[26:27], exec
	s_cselect_b32 s3, s3, s6
	v_writelane_b32 v255, s3, 4
	s_mov_b32 s3, 0xffffffe
	v_and_or_b32 v2, v2, s3, v3
	v_lshrrev_b32_e32 v3, 4, v197
	v_lshlrev_b32_e32 v2, 4, v2
	v_and_b32_e32 v3, 12, v3
	v_and_b32_e32 v4, 3, v88
	v_and_b32_e32 v0, 56, v0
	v_or3_b32 v3, v2, v3, v4
	s_movk_i32 s3, 0xa0
	v_mul_lo_u32 v201, v3, s3
	s_add_i32 s4, 0, 0x10800
	v_lshlrev_b32_e32 v2, 1, v0
	v_mul_lo_u32 v206, v88, s3
	s_add_i32 s3, 0, 0x13000
	v_and_b32_e32 v198, 63, v197
	v_bfe_u32 v1, v197, 4, 2
	v_add3_u32 v202, s4, v201, v2
	v_and_b32_e32 v4, 15, v197
	v_add3_u32 v207, s3, v206, v2
	v_lshlrev_b32_e32 v2, 6, v197
	v_mul_u32_u24_e32 v204, 0xa0, v4
	v_or_b32_e32 v4, 48, v198
	v_and_b32_e32 v209, 0x300, v2
	v_lshlrev_b32_e32 v2, 3, v1
	v_mul_u32_u24_e32 v205, 0xa0, v4
	v_or_b32_e32 v4, 1, v2
	v_cvt_f32_ubyte0_e32 v213, v4
	v_or_b32_e32 v4, 3, v2
	v_cvt_f32_ubyte0_e32 v217, v4
	v_or_b32_e32 v4, 5, v2
	v_cvt_f32_ubyte0_e32 v101, v4
	v_or_b32_e32 v4, 7, v2
	v_cvt_f32_ubyte0_e32 v103, v4
	v_or_b32_e32 v4, 33, v2
	v_cvt_f32_ubyte0_e32 v105, v4
	v_or_b32_e32 v4, 35, v2
	v_cvt_f32_ubyte0_e32 v107, v4
	v_or_b32_e32 v4, 37, v2
	v_cvt_f32_ubyte0_e32 v109, v4
	v_or_b32_e32 v4, 39, v2
	v_cvt_f32_ubyte0_e32 v111, v4
	v_bfe_u32 v4, v197, 1, 5
	v_and_b32_e32 v214, 24, v4
	v_lshlrev_b32_e32 v6, 4, v4
	v_lshlrev_b32_e32 v7, 4, v214
	v_or_b32_e32 v8, 0x270, v6
	v_or_b32_e32 v10, 16, v7
	v_or_b32_e32 v6, 0x70, v6
	v_cvt_f32_u32_e32 v115, v10
	v_or_b32_e32 v10, 48, v7
	v_cvt_f32_u32_e32 v121, v6
	v_or_b32_e32 v6, 0x210, v7
	v_cvt_f32_u32_e32 v117, v10
	v_or_b32_e32 v10, 0x50, v7
	v_cvt_f32_u32_e32 v123, v6
	v_or_b32_e32 v6, 0x230, v7
	v_cvt_f32_u32_e32 v119, v10
	v_or_b32_e32 v10, 0x60, v7
	v_cvt_f32_u32_e32 v125, v6
	v_or_b32_e32 v6, 0x250, v7
	v_or_b32_e32 v5, 2, v2
	v_or_b32_e32 v11, 32, v7
	v_cvt_f32_u32_e32 v120, v10
	v_or_b32_e32 v10, 0x200, v7
	v_cvt_f32_u32_e32 v127, v6
	v_or_b32_e32 v6, 1, v214
	v_cvt_f32_ubyte0_e32 v216, v5
	v_or_b32_e32 v5, 4, v2
	v_or_b32_e32 v9, 0x260, v7
	v_cvt_f32_u32_e32 v114, v7
	v_cvt_f32_u32_e32 v116, v11
	v_or_b32_e32 v11, 64, v7
	v_cvt_f32_u32_e32 v122, v10
	v_or_b32_e32 v10, 0x220, v7
	v_or_b32_e32 v7, 0x240, v7
	v_cvt_f32_ubyte0_e32 v131, v6
	v_or_b32_e32 v6, 3, v214
	v_cvt_f32_ubyte0_e32 v100, v5
	v_or_b32_e32 v5, 6, v2
	v_cvt_f32_u32_e32 v126, v7
	v_or_b32_e32 v7, 2, v214
	v_cvt_f32_ubyte0_e32 v133, v6
	v_or_b32_e32 v6, 5, v214
	v_cvt_f32_ubyte0_e32 v102, v5
	v_or_b32_e32 v5, 32, v2
	v_cvt_f32_ubyte0_e32 v132, v7
	v_or_b32_e32 v7, 4, v214
	v_cvt_f32_ubyte0_e32 v135, v6
	v_or_b32_e32 v6, 7, v4
	v_cvt_f32_ubyte0_e32 v104, v5
	v_or_b32_e32 v5, 34, v2
	v_cvt_f32_ubyte0_e32 v134, v7
	v_or_b32_e32 v7, 6, v214
	v_cvt_f32_ubyte0_e32 v137, v6
	v_or_b32_e32 v6, 33, v214
	v_cvt_f32_ubyte0_e32 v106, v5
	v_or_b32_e32 v5, 36, v2
	v_cvt_f32_u32_e32 v118, v11
	v_cvt_f32_u32_e32 v124, v10
	v_cvt_f32_u32_e32 v129, v8
	v_cvt_f32_u32_e32 v128, v9
	v_cvt_f32_ubyte0_e32 v136, v7
	v_or_b32_e32 v7, 32, v214
	v_cvt_f32_ubyte0_e32 v139, v6
	v_or_b32_e32 v6, 35, v214
	v_bfe_u32 v199, v197, 2, 2
	v_cvt_f32_ubyte0_e32 v108, v5
	v_or_b32_e32 v5, 38, v2
	s_movk_i32 s3, 0x50
	v_cvt_f32_ubyte0_e32 v138, v7
	v_or_b32_e32 v7, 34, v214
	v_cvt_f32_ubyte0_e32 v141, v6
	v_or_b32_e32 v6, 37, v214
	v_or_b32_e32 v4, 39, v4
	s_mov_b32 s22, s21
	s_mov_b32 s23, s21
	v_and_b32_e32 v200, 3, v197
	v_ashrrev_i32_e32 v89, 31, v88
	v_lshlrev_b32_e32 v208, 1, v1
	v_lshlrev_b32_e32 v210, 7, v1
	v_cmp_eq_u32_e64 s[8:9], 0, v198
	v_cvt_f32_ubyte0_e32 v110, v5
	v_mul_lo_u32 v3, v3, s3
	v_mul_lo_u32 v5, v88, s3
	v_cvt_f32_ubyte0_e32 v140, v7
	v_or_b32_e32 v7, 36, v214
	v_cvt_f32_ubyte0_e32 v143, v6
	v_or_b32_e32 v6, 38, v214
	v_cvt_f32_ubyte0_e32 v145, v4
	v_lshlrev_b32_e32 v4, 2, v1
	v_sub_u32_e32 v1, v214, v199
	s_mov_b32 s20, s21
	v_mov_b64_e32 v[98:99], s[22:23]
	v_lshlrev_b64 v[90:91], 7, v[88:89]
	v_mov_b32_e32 v93, 0
	v_add_u32_e32 v203, 64, v88
	v_lshlrev_b64 v[94:95], 11, v[88:89]
	v_cmp_eq_u32_e64 s[6:7], 0, v200
	v_or_b32_e32 v254, 0xc0, v198
	v_cvt_f32_ubyte0_e32 v212, v2
	v_lshlrev_b64 v[112:113], 15, v[88:89]
	s_movk_i32 s78, 0x200
	v_lshl_add_u32 v215, v214, 1, s4
	v_cvt_f32_ubyte0_e32 v130, v214
	v_cvt_f32_ubyte0_e32 v142, v7
	v_cvt_f32_ubyte0_e32 v144, v6
	v_mul_u32_u24_e32 v220, 12, v198
	v_sub_u32_e32 v211, 0, v199
	v_add_u32_e32 v218, -4, v1
	v_sub_u32_e32 v219, v199, v214
	v_lshlrev_b32_e32 v146, 1, v2
	s_movk_i32 s79, 0x1600
	v_mov_b64_e32 v[96:97], s[20:21]
	s_mov_b32 s22, 0x3fb8aa3b
	s_movk_i32 s23, 0xff
	s_xor_b64 s[28:29], s[8:9], -1
	s_add_i32 s81, 0, 0x1a810
	s_add_i32 s82, 0, 0x1a820
	s_add_i32 s83, 0, 0x1a830
	s_add_i32 s84, 0, 0x1a840
	s_add_i32 s85, 0, 0x1a850
	s_add_i32 s86, 0, 0x1a860
	s_add_i32 s87, 0, 0x1a870
	s_add_i32 s88, 0, 0x1a880
	s_add_i32 s89, 0, 0x1a890
	s_add_i32 s90, 0, 0x1a8a0
	s_add_i32 s91, 0, 0x1a8b0
	s_add_i32 s92, 0, 0x1a8c0
	s_add_i32 s93, 0, 0x1a8d0
	s_add_i32 s94, 0, 0x1a8e0
	s_add_i32 s95, 0, 0x1a8f0
	v_lshlrev_b32_e32 v92, 1, v0
	v_lshlrev_b32_e32 v221, 1, v3
	v_lshlrev_b32_e32 v222, 1, v5
	s_movk_i32 s96, 0xfdff
	v_lshlrev_b32_e32 v148, 1, v4
	s_mov_b64 s[30:31], 0xcc00800
	s_mov_b32 s97, 0xcc00000
	v_mov_b32_e32 v223, 0x42800000
	v_not_b32_e32 v224, 63
	v_mov_b32_e32 v225, 0xff800000
	s_mov_b32 s3, 0
	s_branch .LBB0_898

; #define LAS __attribute__((address_space(3)))
; __device__ __forceinline__ f32x4 mfma16(bf16x8 a, bf16x8 b, f32x4 c) { return __builtin_amdgcn_mfma_f32_16x16x32_bf16(a, b, c, 0, 0, 0); }
; template <int MODE>
; __device__ __forceinline__ void nsa_soft(f32x4 (&st)[4], const float (&Bl)[16], float cl, bool fast, int keybase, int t, bool sel, float& m2, float& l, f32x4 (&o)[4], float lfin, LAS float* imp, int lane) {
;     const int kg = lane >> 4;
; #pragma unroll
;     for (int tau = 0; tau < 4; ++tau)
; #pragma unroll
;         for (int r = 0; r < 4; ++r) st[tau][r] = __builtin_fmaf(st[tau][r], LOG2E, Bl[tau * 4 + r]);
;     if (!fast) {
; #pragma unroll
;         for (int tau = 0; tau < 4; ++tau)
; #pragma unroll
;             for (int r = 0; r < 4; ++r) { const int off = keybase + 32 * (tau >> 1) + 8 * kg + 4 * (tau & 1) + r;
;                 int dist; bool valid;
;                 if (MODE <= 1) { dist = t - (16 * off + 31); valid = dist >= 0; }
;                 else if (MODE == 2) { dist = t - off; valid = sel && dist >= 0; }
;                 else { dist = t - off; valid = dist >= 0 && dist < 512; }
;                 st[tau][r] = valid ? st[tau][r] : -INFINITY; }
;     }
; template <int MODE> ...
;     const int kg = lane >> 4;
;     f32x4 st[2][4];
;     { const int rho = lane & 15, dof = kg * 8;
; #pragma unroll
;       for (int tau = 0; tau < 4; ++tau) { const LAS bf16* rp = kt + (16 * tau + rho) * KT_LD + dof;
;           const bf16x8 k0 = *(const LAS bf16x8*)(rp), k1 = *(const LAS bf16x8*)(rp + 32);
; #pragma unroll
;           for (int s = 0; s < 2; ++s) { st[s][tau] = (f32x4){0.f, 0.f, 0.f, 0.f}; st[s][tau] = mfma16(k0, qf[s][0], st[s][tau]); st[s][tau] = mfma16(k1, qf[s][1], st[s][tau]); } } }
.LBB0_907:
	s_bitcmp1_b32 s44, 0
	s_cselect_b32 s40, 0x5000, 0
	v_add_u32_e32 v53, s40, v215
	v_add_u32_e32 v62, v53, v204
	ds_read_b128 v[28:31], v62
	ds_read_b128 v[32:35], v62 offset:64
	v_add_u32_e32 v53, v53, v205
	s_cmp_gt_i32 s45, s4
	s_cselect_b64 s[40:41], -1, 0
	s_waitcnt lgkmcnt(0)
	v_mfma_f32_16x16x32_bf16 v[36:39], v[28:31], v[0:3], 0
	s_cmp_le_i32 s45, s4
	v_mfma_f32_16x16x32_bf16 v[28:31], v[28:31], v[8:11], 0
	v_mfma_f32_16x16x32_bf16 v[40:43], v[32:35], v[4:7], v[36:39]
	s_nop 4
	ds_read_b128 v[36:39], v62 offset:2560
	v_mfma_f32_16x16x32_bf16 v[28:31], v[32:35], v[12:15], v[28:31]
	ds_read_b128 v[32:35], v62 offset:2624
	ds_read_b128 v[58:61], v62 offset:5120
	ds_read_b128 v[62:65], v62 offset:5184
	ds_read_b128 v[70:73], v53
	ds_read_b128 v[74:77], v53 offset:64
	s_waitcnt lgkmcnt(5)
	v_mfma_f32_16x16x32_bf16 v[54:57], v[36:39], v[0:3], 0
	v_add_u32_e32 v53, s45, v210
	v_add_u32_e32 v66, 0xfffffbf1, v53
	v_or_b32_e32 v177, 47, v66
	v_mfma_f32_16x16x32_bf16 v[36:39], v[36:39], v[8:11], 0
	v_or_b32_e32 v180, 31, v66
	v_or_b32_e32 v176, 0x4f, v66
	v_or_b32_e32 v179, 63, v66
	s_waitcnt lgkmcnt(4)
	v_mfma_f32_16x16x32_bf16 v[54:57], v[32:35], v[4:7], v[54:57]
	v_or_b32_e32 v163, 0x6f, v66
	v_or_b32_e32 v178, 0x5f, v66
	v_or_b32_e32 v157, 0x22f, v66
	v_mfma_f32_16x16x32_bf16 v[32:35], v[32:35], v[12:15], v[36:39]
	v_or_b32_e32 v175, 0x21f, v66
	v_or_b32_e32 v156, 0x24f, v66
	v_or_b32_e32 v165, 0x23f, v66
	s_waitcnt lgkmcnt(3)
	v_mfma_f32_16x16x32_bf16 v[36:39], v[58:61], v[0:3], 0
	v_or_b32_e32 v149, 0x26f, v66
	v_or_b32_e32 v158, 0x25f, v66
	v_pk_fma_f32 v[68:69], v[40:41], s[22:23], v[80:81] op_sel_hi:[1,0,1]
	s_waitcnt lgkmcnt(2)
	v_mfma_f32_16x16x32_bf16 v[182:185], v[62:65], v[4:7], v[36:39]
	v_fma_f32 v66, v42, s22, v82
	v_fma_f32 v67, v43, s22, v83
	v_add_u32_e32 v174, 0xfffffc70, v53
	v_add_u32_e32 v159, 0xfffffc80, v53
	v_mfma_f32_16x16x32_bf16 v[36:39], v[58:61], v[8:11], 0
	v_add_u32_e32 v155, 0xfffffe70, v53
	v_add_u32_e32 v147, 0xfffffe80, v53
	s_waitcnt lgkmcnt(1)
	v_mfma_f32_16x16x32_bf16 v[58:61], v[70:73], v[0:3], 0
	v_mfma_f32_16x16x32_bf16 v[40:43], v[70:73], v[8:11], 0
	s_waitcnt lgkmcnt(0)
	v_mfma_f32_16x16x32_bf16 v[186:189], v[74:77], v[4:7], v[58:61]
	v_mfma_f32_16x16x32_bf16 v[36:39], v[62:65], v[12:15], v[36:39]
	v_fma_f32 v64, v54, s22, v84
	v_fma_f32 v65, v55, s22, v85
	v_pk_fma_f32 v[62:63], v[56:57], s[22:23], v[86:87] op_sel_hi:[1,0,1]
	s_nop 0
	v_pk_fma_f32 v[60:61], v[182:183], s[22:23], v[166:167] op_sel_hi:[1,0,1]
	v_mfma_f32_16x16x32_bf16 v[40:43], v[74:77], v[12:15], v[40:43]
	v_fma_f32 v58, v184, s22, v168
	v_fma_f32 v59, v185, s22, v169
	v_pk_fma_f32 v[56:57], v[186:187], s[22:23], v[170:171] op_sel_hi:[1,0,1]
	v_pk_fma_f32 v[54:55], v[188:189], s[22:23], v[172:173] op_sel_hi:[1,0,1]
	s_cbranch_scc1 .LBB0_909
	v_cmp_ge_i32_e32 vcc, v20, v180
	s_nop 1
	v_cndmask_b32_e32 v68, v225, v68, vcc
	v_cmp_ge_i32_e32 vcc, v21, v177
	s_nop 1
	v_cndmask_b32_e32 v69, v225, v69, vcc
	v_cmp_ge_i32_e32 vcc, v22, v179
	s_nop 1
	v_cndmask_b32_e32 v66, v225, v66, vcc
	v_cmp_ge_i32_e32 vcc, v23, v176
	s_nop 1
	v_cndmask_b32_e32 v67, v225, v67, vcc
	v_cmp_ge_i32_e32 vcc, v162, v178
	s_nop 1
	v_cndmask_b32_e32 v64, v225, v64, vcc
	v_cmp_ge_i32_e32 vcc, v51, v163
	s_nop 1
	v_cndmask_b32_e32 v65, v225, v65, vcc
	v_cmp_ge_i32_e32 vcc, v162, v174
	s_nop 1
	v_cndmask_b32_e32 v62, v225, v62, vcc
	v_cmp_ge_i32_e32 vcc, v162, v159
	s_nop 1
	v_cndmask_b32_e32 v63, v225, v63, vcc
	v_cmp_ge_i32_e32 vcc, v20, v175
	s_nop 1
	v_cndmask_b32_e32 v60, v225, v60, vcc
	v_cmp_ge_i32_e32 vcc, v21, v157
	s_nop 1
	v_cndmask_b32_e32 v61, v225, v61, vcc
	v_cmp_ge_i32_e32 vcc, v22, v165
	s_nop 1
	v_cndmask_b32_e32 v58, v225, v58, vcc
	v_cmp_ge_i32_e32 vcc, v23, v156
	s_nop 1
	v_cndmask_b32_e32 v59, v225, v59, vcc
	v_cmp_ge_i32_e32 vcc, v162, v158
	s_nop 1
	v_cndmask_b32_e32 v56, v225, v56, vcc
	v_cmp_ge_i32_e32 vcc, v51, v149
	s_nop 1
	v_cndmask_b32_e32 v57, v225, v57, vcc
	v_cmp_ge_i32_e32 vcc, v162, v155
	s_nop 1
	v_cndmask_b32_e32 v54, v225, v54, vcc
	v_cmp_ge_i32_e32 vcc, v162, v147
	s_nop 1
	v_cndmask_b32_e32 v55, v225, v55, vcc

; #define DB_GLOAD(SK, SV, kb_) do { SK = *(const v4u*)(kbase + (size_t)((kb_) + srow) * ldk + sch); if (MODE != 0) SV = *(const v4u*)(vbase + (size_t)srow * ldv + (kb_) + sch); } while (0)
; #define DB_LWRITE(SK, SV, buf_) do { LAS unsigned char* nb_ = lds + NSA_TILE0 + (buf_) * NSA_TILE_STRIDE; *(LAS v4u*)((LAS bf16*)nb_ + krow * KT_LD + sch) = SK; if (MODE != 0) *(LAS v4u*)((LAS bf16*)(nb_ + NSA_V_OFF) + srow * KT_LD + sch) = SV; } while (0)
; template <int MODE>
; __device__ __forceinline__ void nsa_soft(f32x4 (&st)[4], const float (&Bl)[16], float cl, bool fast, int keybase, int t, bool sel, float& m2, float& l, f32x4 (&o)[4], float lfin, LAS float* imp, int lane) {
;     ...
;         float mloc = fmaxf(fmaxf(fmaxf(st[0][0], st[0][1]), fmaxf(st[0][2], st[0][3])), fmaxf(fmaxf(st[1][0], st[1][1]), fmaxf(st[1][2], st[1][3])));
;         mloc = fmaxf(mloc, fmaxf(fmaxf(fmaxf(st[2][0], st[2][1]), fmaxf(st[2][2], st[2][3])), fmaxf(fmaxf(st[3][0], st[3][1]), fmaxf(st[3][2], st[3][3]))));
;         mloc = xrow16_max(mloc);
; template <int MODE> ...
;     ...
;         if (s + 1 < nst) DB_GLOAD(skA, svA, kb + 64);
;         DB_COMPUTE(kb, s & 1);
;         if (s + 1 < nst) DB_LWRITE(skA, svA, (s + 1) & 1);
.LBB0_911:
	v_max_f32_e32 v36, v75, v75
	v_max_f32_e32 v37, v74, v74
	v_max_f32_e32 v36, v37, v36
	v_max_f32_e32 v37, v71, v71
	v_max_f32_e32 v38, v70, v70
	v_max_f32_e32 v37, v38, v37
	v_max_f32_e32 v38, v35, v35
	v_max_f32_e32 v39, v34, v34
	v_max_f32_e32 v38, v39, v38
	v_max_f32_e32 v39, v33, v33
	v_max_f32_e32 v40, v32, v32
	v_max_f32_e32 v39, v40, v39
	v_max_f32_e32 v40, v29, v29
	v_max_f32_e32 v41, v28, v28
	v_max_f32_e32 v40, v41, v40
	v_max3_f32 v40, v30, v31, v40
	v_max3_f32 v36, v76, v77, v36
	v_max3_f32 v37, v72, v73, v37
	v_max3_f32 v38, v38, v39, v40
	v_max3_f32 v36, v36, v37, v38
	v_mov_b32_e32 v37, v36
	s_nop 1
	v_permlane16_swap_b32_e32 v36, v37
	v_max_f32_e32 v37, v37, v37
	v_max_f32_e32 v36, v36, v36
	v_max_f32_e32 v36, v36, v37
	v_mov_b32_e32 v37, v36
	s_add_i32 s44, s44, 1
	s_andn2_b64 vcc, exec, s[38:39]
	v_permlane32_swap_b32_e32 v36, v37
	s_cbranch_vccnz .LBB0_913
	s_bitcmp1_b32 s44, 0
	s_cselect_b32 s38, 0x5000, 0
	v_add_u32_e32 v38, s38, v202
	s_waitcnt vmcnt(0)
	ds_write_b128 v38, v[16:19]

; #define LAS __attribute__((address_space(3)))
; __device__ __forceinline__ f32x4 mfma16(bf16x8 a, bf16x8 b, f32x4 c) { return __builtin_amdgcn_mfma_f32_16x16x32_bf16(a, b, c, 0, 0, 0); }
; template <int MODE>
; __device__ __forceinline__ void nsa_soft(f32x4 (&st)[4], const float (&Bl)[16], float cl, bool fast, int keybase, int t, bool sel, float& m2, float& l, f32x4 (&o)[4], float lfin, LAS float* imp, int lane) {
;     const int kg = lane >> 4;
; #pragma unroll
;     for (int tau = 0; tau < 4; ++tau)
; #pragma unroll
;         for (int r = 0; r < 4; ++r) st[tau][r] = __builtin_fmaf(st[tau][r], LOG2E, Bl[tau * 4 + r]);
;     if (!fast) {
; #pragma unroll
;         for (int tau = 0; tau < 4; ++tau)
; #pragma unroll
;             for (int r = 0; r < 4; ++r) { const int off = keybase + 32 * (tau >> 1) + 8 * kg + 4 * (tau & 1) + r;
;                 int dist; bool valid;
;                 if (MODE <= 1) { dist = t - (16 * off + 31); valid = dist >= 0; }
;                 else if (MODE == 2) { dist = t - off; valid = sel && dist >= 0; }
;                 else { dist = t - off; valid = dist >= 0 && dist < 512; }
;                 st[tau][r] = valid ? st[tau][r] : -INFINITY; }
;     }
; template <int MODE> ...
;     const int kg = lane >> 4;
;     f32x4 st[2][4];
;     { const int rho = lane & 15, dof = kg * 8;
; #pragma unroll
;       for (int tau = 0; tau < 4; ++tau) { const LAS bf16* rp = kt + (16 * tau + rho) * KT_LD + dof;
;           const bf16x8 k0 = *(const LAS bf16x8*)(rp), k1 = *(const LAS bf16x8*)(rp + 32);
; #pragma unroll
;           for (int s = 0; s < 2; ++s) { st[s][tau] = (f32x4){0.f, 0.f, 0.f, 0.f}; st[s][tau] = mfma16(k0, qf[s][0], st[s][tau]); st[s][tau] = mfma16(k1, qf[s][1], st[s][tau]); } } }
.LBB0_923:
	s_bitcmp1_b32 s49, 0
	s_cselect_b32 s10, 0x5000, 0
	v_add_u32_e32 v190, s10, v215
	v_add_u32_e32 v195, v190, v204
	ds_read_b128 v[64:67], v195
	ds_read_b128 v[68:71], v195 offset:64
	v_add_u32_e32 v226, v190, v205
	s_cmp_gt_i32 s48, s4
	s_cselect_b64 s[40:41], -1, 0
	s_waitcnt lgkmcnt(0)
	v_mfma_f32_16x16x32_bf16 v[72:75], v[64:67], v[0:3], 0
	s_cmp_le_i32 s48, s4
	v_mfma_f32_16x16x32_bf16 v[64:67], v[64:67], v[8:11], 0
	v_mfma_f32_16x16x32_bf16 v[178:181], v[68:71], v[4:7], v[72:75]
	v_mfma_f32_16x16x32_bf16 v[64:67], v[68:71], v[12:15], v[64:67]
	ds_read_b128 v[68:71], v195 offset:2560
	s_nop 2
	ds_read_b128 v[72:75], v195 offset:2624
	s_waitcnt lgkmcnt(1)
	v_mfma_f32_16x16x32_bf16 v[76:79], v[68:71], v[0:3], 0
	v_mfma_f32_16x16x32_bf16 v[68:71], v[68:71], v[8:11], 0
	s_waitcnt lgkmcnt(0)
	v_mfma_f32_16x16x32_bf16 v[182:185], v[72:75], v[4:7], v[76:79]
	v_mfma_f32_16x16x32_bf16 v[68:71], v[72:75], v[12:15], v[68:71]
	ds_read_b128 v[72:75], v195 offset:5120
	s_nop 2
	ds_read_b128 v[76:79], v195 offset:5184
	s_waitcnt lgkmcnt(1)
	v_mfma_f32_16x16x32_bf16 v[186:189], v[72:75], v[0:3], 0
	v_mfma_f32_16x16x32_bf16 v[72:75], v[72:75], v[8:11], 0
	s_waitcnt lgkmcnt(0)
	v_mfma_f32_16x16x32_bf16 v[228:231], v[76:79], v[4:7], v[186:189]
	v_mfma_f32_16x16x32_bf16 v[72:75], v[76:79], v[12:15], v[72:75]
	ds_read_b128 v[76:79], v226
	s_nop 2
	ds_read_b128 v[186:189], v226 offset:64
	s_waitcnt lgkmcnt(1)
	v_mfma_f32_16x16x32_bf16 v[190:193], v[76:79], v[0:3], 0
	v_mfma_f32_16x16x32_bf16 v[76:79], v[76:79], v[8:11], 0
	s_waitcnt lgkmcnt(0)
	v_mfma_f32_16x16x32_bf16 v[248:251], v[186:189], v[4:7], v[190:193]
	v_mfma_f32_16x16x32_bf16 v[76:79], v[186:189], v[12:15], v[76:79]
	v_add_u32_e32 v186, s48, v210
	v_add_u32_e32 v187, 0xfffffbf1, v186
	v_or_b32_e32 v232, 47, v187
	v_or_b32_e32 v237, 31, v187
	v_or_b32_e32 v234, 0x4f, v187
	v_or_b32_e32 v240, 63, v187
	v_or_b32_e32 v233, 0x6f, v187
	v_or_b32_e32 v243, 0x5f, v187
	v_add_u32_e32 v235, 0xfffffc80, v186
	v_add_u32_e32 v241, 0xfffffc70, v186
	v_or_b32_e32 v238, 0x22f, v187
	v_or_b32_e32 v244, 0x21f, v187
	v_or_b32_e32 v236, 0x24f, v187
	v_or_b32_e32 v246, 0x23f, v187
	v_or_b32_e32 v239, 0x26f, v187
	v_or_b32_e32 v245, 0x25f, v187
	v_add_u32_e32 v242, 0xfffffe80, v186
	v_add_u32_e32 v247, 0xfffffe70, v186
	v_pk_fma_f32 v[190:191], v[178:179], s[22:23], v[80:81] op_sel_hi:[1,0,1]
	v_pk_fma_f32 v[192:193], v[180:181], s[22:23], v[82:83] op_sel_hi:[1,0,1]
	v_pk_fma_f32 v[188:189], v[182:183], s[22:23], v[84:85] op_sel_hi:[1,0,1]
	v_pk_fma_f32 v[186:187], v[184:185], s[22:23], v[86:87] op_sel_hi:[1,0,1]
	v_pk_fma_f32 v[184:185], v[228:229], s[22:23], v[166:167] op_sel_hi:[1,0,1]
	v_pk_fma_f32 v[182:183], v[230:231], s[22:23], v[168:169] op_sel_hi:[1,0,1]
	v_pk_fma_f32 v[180:181], v[248:249], s[22:23], v[170:171] op_sel_hi:[1,0,1]
	v_pk_fma_f32 v[178:179], v[250:251], s[22:23], v[172:173] op_sel_hi:[1,0,1]
	s_cbranch_scc1 .LBB0_925
	v_cmp_ge_i32_e32 vcc, v56, v237
	s_nop 1
	v_cndmask_b32_e32 v190, v225, v190, vcc
	v_cmp_ge_i32_e32 vcc, v57, v232
	s_nop 1
	v_cndmask_b32_e32 v191, v225, v191, vcc
	v_cmp_ge_i32_e32 vcc, v58, v240
	s_nop 1
	v_cndmask_b32_e32 v192, v225, v192, vcc
	v_cmp_ge_i32_e32 vcc, v59, v234
	s_nop 1
	v_cndmask_b32_e32 v193, v225, v193, vcc
	v_cmp_ge_i32_e32 vcc, v162, v243
	s_nop 1
	v_cndmask_b32_e32 v188, v225, v188, vcc
	v_cmp_ge_i32_e32 vcc, v147, v233
	s_nop 1
	v_cndmask_b32_e32 v189, v225, v189, vcc
	v_cmp_ge_i32_e32 vcc, v162, v241
	s_nop 1
	v_cndmask_b32_e32 v186, v225, v186, vcc
	v_cmp_ge_i32_e32 vcc, v147, v235
	s_nop 1
	v_cndmask_b32_e32 v187, v225, v187, vcc
	v_cmp_ge_i32_e32 vcc, v56, v244
	s_nop 1
	v_cndmask_b32_e32 v184, v225, v184, vcc
	v_cmp_ge_i32_e32 vcc, v57, v238
	s_nop 1
	v_cndmask_b32_e32 v185, v225, v185, vcc
	v_cmp_ge_i32_e32 vcc, v58, v246
	s_nop 1
	v_cndmask_b32_e32 v182, v225, v182, vcc
	v_cmp_ge_i32_e32 vcc, v59, v236
	s_nop 1
	v_cndmask_b32_e32 v183, v225, v183, vcc
	v_cmp_ge_i32_e32 vcc, v162, v245
	s_nop 1
	v_cndmask_b32_e32 v180, v225, v180, vcc
	v_cmp_ge_i32_e32 vcc, v147, v239
	s_nop 1
	v_cndmask_b32_e32 v181, v225, v181, vcc
	v_cmp_ge_i32_e32 vcc, v162, v247
	s_nop 1
	v_cndmask_b32_e32 v178, v225, v178, vcc
	v_cmp_ge_i32_e32 vcc, v147, v242
	s_nop 1
	v_cndmask_b32_e32 v179, v225, v179, vcc

; #define LAS __attribute__((address_space(3)))
; __device__ __forceinline__ f32x4 mfma16(bf16x8 a, bf16x8 b, f32x4 c) { return __builtin_amdgcn_mfma_f32_16x16x32_bf16(a, b, c, 0, 0, 0); }
; #define DB_GLOAD(SK, SV, kb_) do { SK = *(const v4u*)(kbase + (size_t)((kb_) + srow) * ldk + sch); if (MODE != 0) SV = *(const v4u*)(vbase + (size_t)srow * ldv + (kb_) + sch); } while (0)
; #define DB_LWRITE(SK, SV, buf_) do { LAS unsigned char* nb_ = lds + NSA_TILE0 + (buf_) * NSA_TILE_STRIDE; *(LAS v4u*)((LAS bf16*)nb_ + krow * KT_LD + sch) = SK; if (MODE != 0) *(LAS v4u*)((LAS bf16*)(nb_ + NSA_V_OFF) + srow * KT_LD + sch) = SV; } while (0)
; template <int MODE> ...
;     ...
;     if (MODE != 0) {
;         bf16x8 pb[2][2];
; #pragma unroll
;         for (int s = 0; s < 2; ++s) { pb[s][0] = pack_p(st[s][0], st[s][1]); pb[s][1] = pack_p(st[s][2], st[s][3]); }
; #pragma unroll
;         for (int dt = 0; dt < 4; ++dt) { const LAS bf16* vp = vt + (dt * 16 + (lane & 15)) * KT_LD + 8 * kg;
;             const bf16x8 v0 = *(const LAS bf16x8*)(vp), v1 = *(const LAS bf16x8*)(vp + 32);
; #pragma unroll
;             for (int s = 0; s < 2; ++s) { o[s][dt] = mfma16(v0, pb[s][0], o[s][dt]); o[s][dt] = mfma16(v1, pb[s][1], o[s][dt]); } }
;     }
; template <int MODE> ...
;     ...
;         if (s + 1 < nst) DB_GLOAD(skA, svA, kb + 64);
;         DB_COMPUTE(kb, s & 1);
;         if (s + 1 < nst) DB_LWRITE(skA, svA, (s + 1) & 1);
.LBB0_951:
	s_or_b64 exec, exec, s[10:11]
	v_cvt_pk_bf16_f32 v180, v190, v227
	v_cvt_pk_bf16_f32 v181, v191, v192
	v_cvt_pk_bf16_f32 v182, v188, v189
	v_cvt_pk_bf16_f32 v183, v186, v187
	v_cvt_pk_bf16_f32 v184, v228, v230
	v_cvt_pk_bf16_f32 v185, v229, v231
	v_cvt_pk_bf16_f32 v186, v248, v250
	v_cvt_pk_bf16_f32 v187, v249, v251
	v_cvt_pk_bf16_f32 v74, v73, v74
	v_cvt_pk_bf16_f32 v75, v72, v75
	v_cvt_pk_bf16_f32 v76, v76, v78
	v_cvt_pk_bf16_f32 v77, v77, v79
	v_cvt_pk_bf16_f32 v70, v70, v71
	v_cvt_pk_bf16_f32 v71, v68, v69
	v_cvt_pk_bf16_f32 v72, v64, v178
	v_cvt_pk_bf16_f32 v73, v65, v66
	ds_read_b128 v[64:67], v195 offset:10240
	ds_read_b128 v[188:191], v195 offset:10304
	s_waitcnt lgkmcnt(1)
	v_mfma_f32_16x16x32_bf16 v[44:47], v[64:67], v[180:183], v[44:47]
	s_add_i32 s49, s49, 1
	s_andn2_b64 vcc, exec, s[38:39]
	v_mfma_f32_16x16x32_bf16 v[40:43], v[64:67], v[74:77], v[40:43]
	ds_read_b128 v[64:67], v195 offset:12800
	s_waitcnt lgkmcnt(1)
	v_mfma_f32_16x16x32_bf16 v[44:47], v[188:191], v[184:187], v[44:47]
	v_mfma_f32_16x16x32_bf16 v[40:43], v[188:191], v[70:73], v[40:43]
	ds_read_b128 v[188:191], v195 offset:12864
	s_waitcnt lgkmcnt(1)
	v_mfma_f32_16x16x32_bf16 v[36:39], v[64:67], v[180:183], v[36:39]
	v_mfma_f32_16x16x32_bf16 v[28:31], v[64:67], v[74:77], v[28:31]
	ds_read_b128 v[64:67], v195 offset:15360
	s_waitcnt lgkmcnt(1)
	v_mfma_f32_16x16x32_bf16 v[36:39], v[188:191], v[184:187], v[36:39]
	v_mfma_f32_16x16x32_bf16 v[28:31], v[188:191], v[70:73], v[28:31]
	ds_read_b128 v[188:191], v195 offset:15424
	s_waitcnt lgkmcnt(1)
	v_mfma_f32_16x16x32_bf16 v[32:35], v[64:67], v[180:183], v[32:35]
	v_mfma_f32_16x16x32_bf16 v[20:23], v[64:67], v[74:77], v[20:23]
	ds_read_b128 v[64:67], v226 offset:10240
	s_waitcnt lgkmcnt(1)
	v_mfma_f32_16x16x32_bf16 v[32:35], v[188:191], v[184:187], v[32:35]
	v_mfma_f32_16x16x32_bf16 v[20:23], v[188:191], v[70:73], v[20:23]
	ds_read_b128 v[188:191], v226 offset:10304
	s_waitcnt lgkmcnt(1)
	v_mfma_f32_16x16x32_bf16 v[24:27], v[64:67], v[180:183], v[24:27]
	v_mfma_f32_16x16x32_bf16 v[16:19], v[64:67], v[74:77], v[16:19]
	s_waitcnt lgkmcnt(0)
	v_mfma_f32_16x16x32_bf16 v[24:27], v[188:191], v[184:187], v[24:27]
	v_mfma_f32_16x16x32_bf16 v[16:19], v[188:191], v[70:73], v[16:19]
	s_cbranch_vccnz .LBB0_920
	s_bitcmp1_b32 s49, 0
	s_cselect_b32 s10, 0x5000, 0
	s_add_i32 s10, s10, 0
	s_add_i32 s10, s10, 0x10800
	v_add3_u32 v65, s10, v201, v92
	v_add3_u32 v64, s10, v206, v92
	s_waitcnt vmcnt(0)
	ds_write_b128 v65, v[48:51]
	ds_write_b128 v64, v[52:55] offset:10240
	s_branch .LBB0_920

; #define LAS __attribute__((address_space(3)))
; #define BAR_LDS() do { asm volatile("s_waitcnt lgkmcnt(0)" ::: "memory"); __builtin_amdgcn_s_barrier(); asm volatile("" ::: "memory"); } while (0)
; #define NSA_GATE(s_, br_) sigm(bf2f(((const bf16*)(fresh_args()->ws + WS_R + R_U2))[(rowb + t[s_]) * U2_LD + U2_G + (br_) * 16 + head]))
; __device__ __forceinline__ void nsa_block(LAS unsigned char* lds, int b, int g, int t0b, int tid) {
;     ...
;         for (int s = 0; s < 2; ++s)
; #pragma unroll
;             for (int dt = 0; dt < 4; ++dt) o[s][dt] = o[s][dt] * NSA_GATE(s, 0);
;     ...
; #pragma unroll
;     for (int s = 0; s < 2; ++s)
; #pragma unroll
;         for (int dt = 0; dt < 4; ++dt) RES[(s * 4 + dt) * 64 + lane] = o[s][dt];
;     LAS u64* XCH = (LAS u64*)(lds + NSA_XCH);
;     if (lane == 0) { XCH[wave * 4 + 0] = w0; XCH[wave * 4 + 1] = w1; XCH[wave * 4 + 2] = w2; XCH[wave * 4 + 3] = w3; }
;     BAR_LDS();
;     u64 u0 = 0ull, u1 = 0ull, u2 = 0ull, u3 = 0ull;
; #pragma unroll
;     for (int w = 0; w < 8; ++w) { u0 |= XCH[w * 4 + 0]; u1 |= XCH[w * 4 + 1]; u2 |= XCH[w * 4 + 2]; u3 |= XCH[w * 4 + 3]; }
;     u0 = ((u64)__builtin_amdgcn_readfirstlane((unsigned)(u0 >> 32)) << 32) | (u64)__builtin_amdgcn_readfirstlane((unsigned)u0);
;     u1 = ((u64)__builtin_amdgcn_readfirstlane((unsigned)(u1 >> 32)) << 32) | (u64)__builtin_amdgcn_readfirstlane((unsigned)u1);
;     u2 = ((u64)__builtin_amdgcn_readfirstlane((unsigned)(u2 >> 32)) << 32) | (u64)__builtin_amdgcn_readfirstlane((unsigned)u2);
;     u3 = ((u64)__builtin_amdgcn_readfirstlane((unsigned)(u3 >> 32)) << 32) | (u64)__builtin_amdgcn_readfirstlane((unsigned)u3);
.LBB0_1011:
	s_waitcnt vmcnt(0)
	v_lshlrev_b32_e32 v49, 16, v49
	v_mul_f32_e32 v49, 0xbfb8aa3b, v49
	v_lshlrev_b32_e32 v50, 16, v50
	v_exp_f32_e32 v49, v49
	v_mul_f32_e32 v50, 0xbfb8aa3b, v50
	v_lshlrev_b32_e32 v51, 16, v51
	v_exp_f32_e32 v57, v50
	v_mul_f32_e32 v51, 0xbfb8aa3b, v51
	v_exp_f32_e32 v51, v51
	v_add_f32_e32 v49, 1.0, v49
	v_lshlrev_b32_e32 v52, 16, v52
	v_rcp_f32_e32 v50, v49
	v_add_f32_e32 v49, 1.0, v57
	v_mul_f32_e32 v52, 0xbfb8aa3b, v52
	v_exp_f32_e32 v57, v52
	v_rcp_f32_e32 v52, v49
	v_add_f32_e32 v49, 1.0, v51
	v_lshlrev_b32_e32 v51, 16, v53
	v_mul_f32_e32 v51, 0xbfb8aa3b, v51
	v_lshlrev_b32_e32 v53, 16, v54
	v_exp_f32_e32 v51, v51
	v_mul_f32_e32 v53, 0xbfb8aa3b, v53
	v_exp_f32_e32 v53, v53
	v_rcp_f32_e32 v58, v49
	v_add_f32_e32 v49, 1.0, v57
	v_rcp_f32_e32 v54, v49
	v_add_f32_e32 v49, 1.0, v51
	v_lshlrev_b32_e32 v51, 16, v55
	v_rcp_f32_e32 v60, v49
	v_add_f32_e32 v49, 1.0, v53
	v_mul_f32_e32 v51, 0xbfb8aa3b, v51
	v_lshlrev_b32_e32 v53, 16, v56
	v_exp_f32_e32 v51, v51
	v_mul_f32_e32 v53, 0xbfb8aa3b, v53
	v_exp_f32_e32 v53, v53
	v_rcp_f32_e32 v56, v49
	v_add_f32_e32 v49, 1.0, v51
	v_rcp_f32_e32 v62, v49
	v_add_f32_e32 v49, 1.0, v53
	v_rcp_f32_e32 v64, v49
	v_pk_mul_f32 v[46:47], v[46:47], v[50:51] op_sel_hi:[1,0]
	v_pk_mul_f32 v[44:45], v[44:45], v[50:51] op_sel_hi:[1,0]
	v_add_u32_e32 v89, v48, v220
	v_pk_mul_f32 v[38:39], v[38:39], v[52:53] op_sel_hi:[1,0]
	v_pk_mul_f32 v[36:37], v[36:37], v[52:53] op_sel_hi:[1,0]
	v_pk_mul_f32 v[34:35], v[34:35], v[58:59] op_sel_hi:[1,0]
	v_pk_mul_f32 v[32:33], v[32:33], v[58:59] op_sel_hi:[1,0]
	v_pk_mul_f32 v[26:27], v[26:27], v[54:55] op_sel_hi:[1,0]
	v_pk_mul_f32 v[24:25], v[24:25], v[54:55] op_sel_hi:[1,0]
	v_pk_mul_f32 v[42:43], v[42:43], v[60:61] op_sel_hi:[1,0]
	v_pk_mul_f32 v[40:41], v[40:41], v[60:61] op_sel_hi:[1,0]
	v_pk_mul_f32 v[30:31], v[30:31], v[56:57] op_sel_hi:[1,0]
	v_pk_mul_f32 v[28:29], v[28:29], v[56:57] op_sel_hi:[1,0]
	v_pk_mul_f32 v[22:23], v[22:23], v[62:63] op_sel_hi:[1,0]
	v_pk_mul_f32 v[20:21], v[20:21], v[62:63] op_sel_hi:[1,0]
	v_pk_mul_f32 v[18:19], v[18:19], v[64:65] op_sel_hi:[1,0]
	v_pk_mul_f32 v[16:17], v[16:17], v[64:65] op_sel_hi:[1,0]
	ds_write_b128 v89, v[44:47]
	ds_write_b128 v89, v[36:39] offset:1024
	ds_write_b128 v89, v[32:35] offset:2048
	ds_write_b128 v89, v[24:27] offset:3072
	ds_write_b128 v89, v[40:43] offset:4096
	ds_write_b128 v89, v[28:31] offset:5120
	ds_write_b128 v89, v[20:23] offset:6144
	ds_write_b128 v89, v[16:19] offset:7168
	s_and_saveexec_b64 s[10:11], s[8:9]
	s_cbranch_execz .LBB0_1013
	s_lshl_b32 s12, s43, 5
	s_add_i32 s12, s12, 0
	s_add_i32 s12, s12, 0x1a800
	v_mov_b32_e32 v16, s16
	v_mov_b32_e32 v17, s17
	v_mov_b32_e32 v18, s38
	v_mov_b32_e32 v19, s39
	v_mov_b32_e32 v20, s12
	ds_write_b128 v20, v[16:19]
	v_mov_b32_e32 v16, s40
	v_mov_b32_e32 v17, s41
	v_mov_b32_e32 v18, s44
	v_mov_b32_e32 v19, s45
	ds_write_b128 v20, v[16:19] offset:16
.LBB0_1013:
	s_or_b64 exec, exec, s[10:11]
	s_add_i32 s10, 0, 0x1a800
	s_waitcnt lgkmcnt(0)
	s_barrier
	v_mov_b32_e32 v16, s10
	v_mov_b32_e32 v20, s82
	ds_read_b128 v[16:19], v16
	ds_read_b128 v[20:23], v20
	v_mov_b32_e32 v24, s81
	v_mov_b32_e32 v28, s83
	ds_read_b128 v[24:27], v24
	ds_read_b128 v[28:31], v28
	s_waitcnt lgkmcnt(2)
	v_or_b32_e32 v32, v20, v16
	v_mov_b32_e32 v16, s84
	v_or_b32_e32 v33, v21, v17
	v_or_b32_e32 v34, v22, v18
	v_or_b32_e32 v35, v23, v19
	ds_read_b128 v[16:19], v16
	v_mov_b32_e32 v20, s85
	s_waitcnt lgkmcnt(1)
	v_or_b32_e32 v24, v28, v24
	ds_read_b128 v[20:23], v20
	v_or_b32_e32 v25, v29, v25
	s_waitcnt lgkmcnt(1)
	v_or_b32_e32 v28, v32, v16
	v_mov_b32_e32 v16, s86
	v_or_b32_e32 v26, v30, v26
	v_or_b32_e32 v27, v31, v27
	v_or_b32_e32 v29, v33, v17
	v_or_b32_e32 v30, v34, v18
	v_or_b32_e32 v31, v35, v19
	ds_read_b128 v[16:19], v16
	s_waitcnt lgkmcnt(1)
	v_or_b32_e32 v24, v24, v20
	v_mov_b32_e32 v20, s87
	v_or_b32_e32 v25, v25, v21
	v_or_b32_e32 v26, v26, v22
	v_or_b32_e32 v27, v27, v23
	ds_read_b128 v[20:23], v20
	s_waitcnt lgkmcnt(1)
	v_or_b32_e32 v28, v28, v16
	v_mov_b32_e32 v16, s88
	v_or_b32_e32 v29, v29, v17
	v_or_b32_e32 v30, v30, v18
	v_or_b32_e32 v31, v31, v19
	ds_read_b128 v[16:19], v16
	s_waitcnt lgkmcnt(1)
	v_or_b32_e32 v24, v24, v20
	v_mov_b32_e32 v20, s89
	v_or_b32_e32 v25, v25, v21
	v_or_b32_e32 v26, v26, v22
	v_or_b32_e32 v27, v27, v23
	ds_read_b128 v[20:23], v20
	s_waitcnt lgkmcnt(1)
	v_or_b32_e32 v28, v28, v16
	v_mov_b32_e32 v16, s90
	v_or_b32_e32 v29, v29, v17
	v_or_b32_e32 v30, v30, v18
	v_or_b32_e32 v31, v31, v19
	ds_read_b128 v[16:19], v16
	s_waitcnt lgkmcnt(1)
	v_or_b32_e32 v24, v24, v20
	v_mov_b32_e32 v20, s91
	v_or_b32_e32 v25, v25, v21
	v_or_b32_e32 v26, v26, v22
	v_or_b32_e32 v27, v27, v23
	ds_read_b128 v[20:23], v20
	s_waitcnt lgkmcnt(1)
	v_or_b32_e32 v28, v28, v16
	v_mov_b32_e32 v16, s92
	v_or_b32_e32 v29, v29, v17
	v_or_b32_e32 v30, v30, v18
	v_or_b32_e32 v31, v31, v19
	ds_read_b128 v[16:19], v16
	s_waitcnt lgkmcnt(1)
	v_or_b32_e32 v24, v24, v20
	v_mov_b32_e32 v20, s93
	v_or_b32_e32 v25, v25, v21
	v_or_b32_e32 v26, v26, v22
	v_or_b32_e32 v27, v27, v23
	ds_read_b128 v[20:23], v20
	s_waitcnt lgkmcnt(1)
	v_or_b32_e32 v28, v28, v16
	v_mov_b32_e32 v16, s94
	v_or_b32_e32 v29, v29, v17
	v_or_b32_e32 v30, v30, v18
	v_or_b32_e32 v31, v31, v19
	ds_read_b128 v[16:19], v16
	s_waitcnt lgkmcnt(1)
	v_or_b32_e32 v24, v24, v20
	v_mov_b32_e32 v20, s95
	v_or_b32_e32 v25, v25, v21
	v_or_b32_e32 v26, v26, v22
	v_or_b32_e32 v27, v27, v23
	ds_read_b128 v[20:23], v20
	s_waitcnt lgkmcnt(1)
	v_or_b32_e32 v16, v28, v16
	v_or_b32_e32 v17, v29, v17
	v_readfirstlane_b32 s10, v16
	s_bfe_i64 s[50:51], s[10:11], 0x200000
	s_mov_b64 s[10:11], s[0:1]
	s_load_dwordx2 s[10:11], s[10:11], 0xa8
	v_readfirstlane_b32 s49, v17
	s_mov_b32 s48, s21
	v_or_b32_e32 v18, v30, v18
	v_or_b32_e32 v19, v31, v19
	s_waitcnt lgkmcnt(0)
	v_or_b32_e32 v20, v24, v20
	v_or_b32_e32 v21, v25, v21
	v_or_b32_e32 v22, v26, v22
	v_or_b32_e32 v23, v27, v23
	s_or_b64 s[48:49], s[50:51], s[48:49]
	v_readfirstlane_b32 s15, v19
	v_readfirstlane_b32 s12, v18
	v_readfirstlane_b32 s47, v21
	v_readfirstlane_b32 s14, v20
	v_readfirstlane_b32 s13, v23
	s_cmp_eq_u64 s[48:49], 0
	v_readfirstlane_b32 s20, v22
	s_cbranch_scc1 .LBB0_1015
	s_add_u32 s50, s48, -1
	s_addc_u32 s51, s49, -1
	s_ff1_i32_b64 s61, s[48:49]
	s_and_b64 s[52:53], s[50:51], s[48:49]
	s_mov_b64 s[54:55], 0
	s_branch .LBB0_1016

; #define LAS __attribute__((address_space(3)))
; __device__ __forceinline__ f32x4 mfma16(bf16x8 a, bf16x8 b, f32x4 c) { return __builtin_amdgcn_mfma_f32_16x16x32_bf16(a, b, c, 0, 0, 0); }
; template <int MODE> ...
;     const int kg = lane >> 4;
;     f32x4 st[2][4];
;     { const int rho = lane & 15, dof = kg * 8;
; #pragma unroll
;       for (int tau = 0; tau < 4; ++tau) { const LAS bf16* rp = kt + (16 * tau + rho) * KT_LD + dof;
;           const bf16x8 k0 = *(const LAS bf16x8*)(rp), k1 = *(const LAS bf16x8*)(rp + 32);
; #pragma unroll
;           for (int s = 0; s < 2; ++s) { st[s][tau] = (f32x4){0.f, 0.f, 0.f, 0.f}; st[s][tau] = mfma16(k0, qf[s][0], st[s][tau]); st[s][tau] = mfma16(k1, qf[s][1], st[s][tau]); } } }
.LBB0_1039:
	s_lshr_b32 s10, s61, 6
	s_cmp_eq_u32 s10, 2
	s_cselect_b32 s11, s41, s45
	s_cselect_b32 s12, s40, s44
	s_cmp_eq_u32 s10, 1
	s_cselect_b32 s12, s38, s12
	s_cselect_b32 s11, s39, s11
	s_cmp_lt_u32 s61, 64
	s_cselect_b32 s13, s17, s11
	s_cselect_b32 s12, s16, s12
	s_lshr_b64 s[12:13], s[12:13], s61
	s_and_b32 s20, s12, 1
	s_cmp_eq_u64 s[20:21], 0
	s_cbranch_scc1 .LBB0_1048
	s_and_b32 s62, s61, 63
	s_bitcmp1_b32 s43, 0
	s_cselect_b32 s11, 0x5000, 0
	v_add_u32_e32 v86, s11, v215
	v_add_u32_e32 v165, v86, v204
	ds_read_b128 v[56:59], v165
	ds_read_b128 v[60:63], v165 offset:64
	ds_read_b128 v[74:77], v165 offset:2560
	v_lshl_add_u32 v68, s10, 3, v147
	v_add_u32_e32 v226, v86, v205
	s_waitcnt lgkmcnt(2)
	v_mfma_f32_16x16x32_bf16 v[64:67], v[56:59], v[0:3], 0
	s_cmp_lt_i32 s61, s19
	s_cselect_b64 s[56:57], -1, 0
	s_cmp_ge_i32 s61, s19
	v_mfma_f32_16x16x32_bf16 v[56:59], v[56:59], v[8:11], 0
	s_cselect_b64 s[58:59], -1, 0
	s_lshl_b32 s20, s61, 6
	v_or_b32_e32 v236, s20, v214
	s_waitcnt lgkmcnt(1)
	v_mfma_f32_16x16x32_bf16 v[70:73], v[60:63], v[4:7], v[64:67]
	v_or_b32_e32 v240, 2, v236
	v_or_b32_e32 v239, 3, v236
	v_or_b32_e32 v238, 5, v236
	v_add_u32_e32 v64, 0x2000, v68
	ds_read2_b64 v[66:69], v64 offset1:16
	v_mfma_f32_16x16x32_bf16 v[56:59], v[60:63], v[12:15], v[56:59]
	ds_read_b128 v[60:63], v165 offset:2624
	ds_read_b128 v[82:85], v165 offset:5184
	v_pk_fma_f32 v[188:189], v[70:71], s[22:23], v[170:171] op_sel_hi:[1,0,1]
	s_waitcnt lgkmcnt(2)
	v_lshrrev_b64 v[64:65], s62, v[66:67]
	v_and_b32_e32 v78, 1, v64
	v_mfma_f32_16x16x32_bf16 v[64:67], v[74:77], v[0:3], 0
	v_cmp_eq_u32_e64 s[10:11], 1, v78
	v_pk_fma_f32 v[86:87], v[72:73], s[22:23], v[172:173] op_sel_hi:[1,0,1]
	v_or_b32_e32 v237, 6, v236
	s_waitcnt lgkmcnt(1)
	v_mfma_f32_16x16x32_bf16 v[78:81], v[60:63], v[4:7], v[64:67]
	v_or_b32_e32 v235, 7, v236
	v_or_b32_e32 v234, 32, v236
	v_or_b32_e32 v233, 33, v236
	ds_read_b128 v[64:67], v165 offset:5120
	v_mfma_f32_16x16x32_bf16 v[74:77], v[74:77], v[8:11], 0
	v_or_b32_e32 v232, 34, v236
	v_or_b32_e32 v227, 39, v236
	s_and_b64 vcc, exec, s[56:57]
	v_mfma_f32_16x16x32_bf16 v[60:63], v[60:63], v[12:15], v[74:77]
	s_nop 3
	ds_read_b128 v[74:77], v226
	ds_read_b128 v[190:193], v226 offset:64
	v_cmp_ge_i32_e64 s[12:13], v162, v236
	s_waitcnt lgkmcnt(2)
	v_mfma_f32_16x16x32_bf16 v[228:231], v[64:67], v[0:3], 0
	v_mfma_f32_16x16x32_bf16 v[64:67], v[64:67], v[8:11], 0
	v_mfma_f32_16x16x32_bf16 v[242:245], v[82:85], v[4:7], v[228:231]
	v_mfma_f32_16x16x32_bf16 v[64:67], v[82:85], v[12:15], v[64:67]
	s_nop 4
	v_or_b32_e32 v231, 35, v236
	v_or_b32_e32 v230, 36, v236
	v_or_b32_e32 v229, 37, v236
	s_waitcnt lgkmcnt(1)
	v_mfma_f32_16x16x32_bf16 v[82:85], v[74:77], v[0:3], 0
	v_or_b32_e32 v228, 38, v236
	s_waitcnt lgkmcnt(0)
	v_mfma_f32_16x16x32_bf16 v[70:73], v[190:193], v[4:7], v[82:85]
	v_mfma_f32_16x16x32_bf16 v[246:249], v[74:77], v[8:11], 0
	s_nop 3
	v_fma_f32 v84, v78, s22, v174
	v_fma_f32 v85, v79, s22, v175
	s_nop 0
	v_pk_fma_f32 v[76:77], v[70:71], s[22:23], v[182:183] op_sel_hi:[1,0,1]
	v_pk_fma_f32 v[74:75], v[72:73], s[22:23], v[184:185] op_sel_hi:[1,0,1]
	v_mfma_f32_16x16x32_bf16 v[70:73], v[190:193], v[12:15], v[246:249]
	v_fma_f32 v82, v80, s22, v176
	v_fma_f32 v83, v81, s22, v177
	v_pk_fma_f32 v[80:81], v[242:243], s[22:23], v[178:179] op_sel_hi:[1,0,1]
	v_pk_fma_f32 v[78:79], v[244:245], s[22:23], v[180:181] op_sel_hi:[1,0,1]
	s_cbranch_vccnz .LBB0_1042
	s_and_b64 vcc, s[10:11], s[12:13]
	v_cndmask_b32_e32 v188, v225, v188, vcc
	v_cmp_gt_i32_e32 vcc, v162, v236
	s_and_b64 vcc, s[10:11], vcc
	v_or_b32_e32 v190, 4, v236
	v_cndmask_b32_e32 v189, v225, v189, vcc
	v_cmp_ge_i32_e32 vcc, v162, v240
	s_and_b64 vcc, s[10:11], vcc
	s_nop 0
	v_cndmask_b32_e32 v86, v225, v86, vcc
	v_cmp_ge_i32_e32 vcc, v162, v239
	s_and_b64 vcc, s[10:11], vcc
	s_nop 0
	v_cndmask_b32_e32 v87, v225, v87, vcc
	v_cmp_ge_i32_e32 vcc, v162, v190
	s_and_b64 vcc, s[10:11], vcc
	s_nop 0
	v_cndmask_b32_e32 v84, v225, v84, vcc
	v_cmp_ge_i32_e32 vcc, v162, v238
	s_and_b64 vcc, s[10:11], vcc
	s_nop 0
	v_cndmask_b32_e32 v85, v225, v85, vcc
	v_cmp_ge_i32_e32 vcc, v162, v237
	s_and_b64 vcc, s[10:11], vcc
	s_nop 0
	v_cndmask_b32_e32 v82, v225, v82, vcc
	v_cmp_ge_i32_e32 vcc, v162, v235
	s_and_b64 vcc, s[10:11], vcc
	s_nop 0
	v_cndmask_b32_e32 v83, v225, v83, vcc
	v_cmp_ge_i32_e32 vcc, v162, v234
	s_and_b64 vcc, s[10:11], vcc
	s_nop 0
	v_cndmask_b32_e32 v80, v225, v80, vcc
	v_cmp_ge_i32_e32 vcc, v162, v233
	s_and_b64 vcc, s[10:11], vcc
	s_nop 0
	v_cndmask_b32_e32 v81, v225, v81, vcc
	v_cmp_ge_i32_e32 vcc, v162, v232
	s_and_b64 vcc, s[10:11], vcc
	s_nop 0
	v_cndmask_b32_e32 v78, v225, v78, vcc
	v_cmp_ge_i32_e32 vcc, v162, v231
	s_and_b64 vcc, s[10:11], vcc
	s_nop 0
	v_cndmask_b32_e32 v79, v225, v79, vcc
	v_cmp_ge_i32_e32 vcc, v162, v230
	s_and_b64 vcc, s[10:11], vcc
	s_nop 0
	v_cndmask_b32_e32 v76, v225, v76, vcc
	v_cmp_ge_i32_e32 vcc, v162, v229
	s_and_b64 vcc, s[10:11], vcc
	s_nop 0
	v_cndmask_b32_e32 v77, v225, v77, vcc
	v_cmp_ge_i32_e32 vcc, v162, v228
	s_and_b64 vcc, s[10:11], vcc
	s_nop 0
	v_cndmask_b32_e32 v74, v225, v74, vcc
	v_cmp_ge_i32_e32 vcc, v162, v227
	s_and_b64 vcc, s[10:11], vcc
	s_nop 0
	v_cndmask_b32_e32 v75, v225, v75, vcc

; #define LAS __attribute__((address_space(3)))
; template <int MODE>
; __device__ __forceinline__ void nsa_soft(f32x4 (&st)[4], const float (&Bl)[16], float cl, bool fast, int keybase, int t, bool sel, float& m2, float& l, f32x4 (&o)[4], float lfin, LAS float* imp, int lane) {
;     ...
;     } else {
;         float mloc = fmaxf(fmaxf(fmaxf(st[0][0], st[0][1]), fmaxf(st[0][2], st[0][3])), fmaxf(fmaxf(st[1][0], st[1][1]), fmaxf(st[1][2], st[1][3])));
;         mloc = fmaxf(mloc, fmaxf(fmaxf(fmaxf(st[2][0], st[2][1]), fmaxf(st[2][2], st[2][3])), fmaxf(fmaxf(st[3][0], st[3][1]), fmaxf(st[3][2], st[3][3]))));
;         mloc = xrow16_max(mloc);
;         const float mnew = fmaxf(m2, mloc + cl); const float alpha = __builtin_amdgcn_exp2f(m2 - mnew); m2 = mnew;
;         const float sh = cl - mnew;
;         float ps = 0.f;
; #pragma unroll
;         for (int tau = 0; tau < 4; ++tau)
; #pragma unroll
;             for (int r = 0; r < 4; ++r) { const float p = __builtin_amdgcn_exp2f(st[tau][r] + sh); st[tau][r] = p; ps += p; }
;         l = l * alpha + ps;
;         if (MODE != 0) {
; #pragma unroll
;             for (int dt = 0; dt < 4; ++dt) o[dt] = o[dt] * alpha;
;         }
; template <int MODE> ...
;     ...
;     if (MODE != 0) {
;         bf16x8 pb[2][2];
; #pragma unroll
;         for (int s = 0; s < 2; ++s) { pb[s][0] = pack_p(st[s][0], st[s][1]); pb[s][1] = pack_p(st[s][2], st[s][3]); }
; #pragma unroll
;         for (int dt = 0; dt < 4; ++dt) { const LAS bf16* vp = vt + (dt * 16 + (lane & 15)) * KT_LD + 8 * kg;
;             const bf16x8 v0 = *(const LAS bf16x8*)(vp), v1 = *(const LAS bf16x8*)(vp + 32);
.LBB0_1044:
	v_sub_u32_e32 v64, s20, v162
	v_cvt_f32_i32_e32 v64, v64
	s_xor_b64 s[10:11], s[10:11], -1
	v_max_f32_e32 v65, v242, v242
	s_and_b64 vcc, s[56:57], s[10:11]
	v_mul_f32_e32 v64, v154, v64
	v_max_f32_e32 v66, v241, v241
	v_cndmask_b32_e32 v64, v64, v225, vcc
	v_max_f32_e32 v65, v65, v66
	v_add_f32_e32 v65, v64, v65
	v_max_f32_e32 v66, v163, v163
	v_max_f32_e32 v227, v66, v65
	v_sub_f32_e32 v64, v64, v227
	v_add_f32_e32 v65, v188, v64
	v_exp_f32_e32 v65, v65
	v_add_f32_e32 v66, v189, v64
	v_exp_f32_e32 v66, v66
	v_add_f32_e32 v67, v86, v64
	v_exp_f32_e32 v67, v67
	v_add_f32_e32 v71, v87, v64
	v_exp_f32_e32 v71, v71
	v_add_f32_e32 v73, v84, v64
	v_add_f32_e32 v70, 0, v65
	v_exp_f32_e32 v73, v73
	v_add_f32_e32 v84, v85, v64
	v_add_f32_e32 v70, v66, v70
	v_exp_f32_e32 v84, v84
	v_add_f32_e32 v82, v82, v64
	v_add_f32_e32 v70, v67, v70
	v_exp_f32_e32 v82, v82
	v_add_f32_e32 v70, v71, v70
	v_add_f32_e32 v70, v73, v70
	v_add_f32_e32 v70, v84, v70
	v_sub_f32_e32 v72, v163, v227
	v_add_f32_e32 v163, v82, v70
	v_add_f32_e32 v70, v83, v64
	v_exp_f32_e32 v83, v70
	v_add_f32_e32 v70, v80, v64
	v_exp_f32_e32 v80, v70
	v_add_f32_e32 v70, v81, v64
	v_exp_f32_e32 v81, v70
	v_add_f32_e32 v70, v78, v64
	v_exp_f32_e32 v78, v70
	v_add_f32_e32 v70, v79, v64
	v_exp_f32_e32 v79, v70
	v_add_f32_e32 v70, v76, v64
	v_exp_f32_e32 v76, v70
	v_add_f32_e32 v70, v77, v64
	v_exp_f32_e32 v77, v70
	v_add_f32_e32 v70, v74, v64
	v_exp_f32_e32 v188, v70
	v_sub_u32_e32 v70, s20, v164
	v_cvt_f32_i32_e32 v70, v70
	v_add_f32_e32 v64, v75, v64
	v_exp_f32_e32 v189, v64
	v_max_f32_e32 v74, v192, v192
	v_mul_f32_e32 v64, v154, v70
	v_max_f32_e32 v70, v193, v193
	v_max_f32_e32 v70, v74, v70
	v_max_f32_e32 v74, v69, v69
	v_max_f32_e32 v75, v68, v68
	v_max_f32_e32 v74, v75, v74
	v_max_f32_e32 v75, v63, v63
	v_max_f32_e32 v85, v62, v62
	v_max_f32_e32 v75, v85, v75
	v_max_f32_e32 v85, v61, v61
	v_max_f32_e32 v86, v60, v60
	v_max_f32_e32 v85, v86, v85
	v_max_f32_e32 v86, v59, v59
	v_max_f32_e32 v87, v58, v58
	v_max_f32_e32 v86, v87, v86
	v_max3_f32 v86, v56, v57, v86
	v_max3_f32 v70, v194, v195, v70
	v_max3_f32 v74, v190, v191, v74
	v_max3_f32 v75, v75, v85, v86
	v_max3_f32 v70, v70, v74, v75
	v_mov_b32_e32 v74, v70
	s_nop 1
	v_permlane16_swap_b32_e32 v70, v74
	v_max_f32_e32 v74, v74, v74
	v_max_f32_e32 v70, v70, v70
	v_max_f32_e32 v70, v70, v74
	v_mov_b32_e32 v74, v70
	s_xor_b64 s[10:11], s[12:13], -1
	s_nop 0
	v_permlane32_swap_b32_e32 v70, v74
	s_and_b64 vcc, s[56:57], s[10:11]
	v_max_f32_e32 v74, v74, v74
	v_max_f32_e32 v70, v70, v70
	v_cndmask_b32_e32 v64, v64, v225, vcc
	v_max_f32_e32 v70, v70, v74
	v_add_f32_e32 v70, v64, v70
	v_max_f32_e32 v74, v161, v161
	v_max_f32_e32 v232, v74, v70
	v_sub_f32_e32 v64, v64, v232
	v_add_f32_e32 v70, v194, v64
	v_exp_f32_e32 v233, v70
	v_add_f32_e32 v70, v195, v64
	v_exp_f32_e32 v195, v70
	v_add_f32_e32 v70, v192, v64
	v_add_f32_e32 v56, v56, v64
	v_exp_f32_e32 v234, v70
	v_add_f32_e32 v70, v193, v64
	v_exp_f32_e32 v244, v56
	v_add_f32_e32 v56, v57, v64
	v_exp_f32_e32 v235, v70
	v_add_f32_e32 v70, v190, v64
	v_add_f32_e32 v68, v68, v64
	v_add_f32_e32 v62, v62, v64
	v_add_f32_e32 v60, v60, v64
	v_exp_f32_e32 v245, v56
	v_add_f32_e32 v56, v58, v64
	v_exp_f32_e32 v236, v70
	v_add_f32_e32 v70, v191, v64
	v_exp_f32_e32 v238, v68
	v_add_f32_e32 v68, v69, v64
	v_exp_f32_e32 v240, v62
	v_add_f32_e32 v62, v63, v64
	v_exp_f32_e32 v242, v60
	v_add_f32_e32 v60, v61, v64
	v_exp_f32_e32 v246, v56
	v_add_f32_e32 v56, v59, v64
	v_exp_f32_e32 v237, v70
	v_exp_f32_e32 v239, v68
	v_exp_f32_e32 v241, v62
	v_exp_f32_e32 v243, v60
	v_exp_f32_e32 v247, v56
	v_cvt_pk_bf16_f32 v68, v65, v66
	v_cvt_pk_bf16_f32 v69, v67, v71
	v_cvt_pk_bf16_f32 v70, v73, v84
	v_cvt_pk_bf16_f32 v71, v82, v83
	v_cvt_pk_bf16_f32 v84, v80, v81
	v_cvt_pk_bf16_f32 v85, v78, v79
	v_cvt_pk_bf16_f32 v86, v76, v77
	v_cvt_pk_bf16_f32 v87, v188, v189
	v_cvt_pk_bf16_f32 v190, v233, v195
	v_cvt_pk_bf16_f32 v191, v234, v235
	v_cvt_pk_bf16_f32 v192, v236, v237
	v_cvt_pk_bf16_f32 v193, v238, v239
	v_cvt_pk_bf16_f32 v228, v240, v241
	v_cvt_pk_bf16_f32 v229, v242, v243
	v_cvt_pk_bf16_f32 v230, v244, v245
	v_cvt_pk_bf16_f32 v231, v246, v247
	ds_read_b128 v[56:59], v165 offset:10240
	v_add_f32_e32 v60, v83, v163
	v_exp_f32_e32 v64, v72
	v_add_f32_e32 v65, v80, v60
	ds_read_b128 v[60:63], v165 offset:10304
	v_add_f32_e32 v65, v81, v65
	v_pk_mul_f32 v[54:55], v[54:55], v[64:65] op_sel_hi:[1,0]
	v_pk_mul_f32 v[52:53], v[52:53], v[64:65] op_sel_hi:[1,0]
	v_sub_f32_e32 v66, v161, v232
	v_exp_f32_e32 v194, v66
	s_waitcnt lgkmcnt(1)
; #define LAS __attribute__((address_space(3)))
; __device__ __forceinline__ f32x4 mfma16(bf16x8 a, bf16x8 b, f32x4 c) { return __builtin_amdgcn_mfma_f32_16x16x32_bf16(a, b, c, 0, 0, 0); }
; #define SL_GLOAD(SK, SV, j_) do { SK = *(const v4u*)(ksb + (size_t)((j_) * 64 + srow) * U2_LD + sch); SV = *(const v4u*)(vsb + (size_t)srow * SEQ + (j_) * 64 + sch); } while (0)
; #define SL_LWRITE(SK, SV, buf_) do { LAS unsigned char* nb_ = lds + NSA_TILE0 + (buf_) * NSA_TILE_STRIDE; *(LAS v4u*)((LAS bf16*)nb_ + krow * KT_LD + sch) = SK; *(LAS v4u*)((LAS bf16*)(nb_ + NSA_V_OFF) + srow * KT_LD + sch) = SV; } while (0)
; template <int MODE> ...
;     ...
;     if (MODE != 0) {
;         bf16x8 pb[2][2];
; #pragma unroll
;         for (int s = 0; s < 2; ++s) { pb[s][0] = pack_p(st[s][0], st[s][1]); pb[s][1] = pack_p(st[s][2], st[s][3]); }
; #pragma unroll
;         for (int dt = 0; dt < 4; ++dt) { const LAS bf16* vp = vt + (dt * 16 + (lane & 15)) * KT_LD + 8 * kg;
;             const bf16x8 v0 = *(const LAS bf16x8*)(vp), v1 = *(const LAS bf16x8*)(vp + 32);
; #pragma unroll
;             for (int s = 0; s < 2; ++s) { o[s][dt] = mfma16(v0, pb[s][0], o[s][dt]); o[s][dt] = mfma16(v1, pb[s][1], o[s][dt]); } }
;     }
; __device__ __forceinline__ void nsa_block(LAS unsigned char* lds, int b, int g, int t0b, int tid) {
;     ...
;             if (jn >= 0) SL_GLOAD(skA, svA, jn);
;             SL_COMPUTE(jc, sidx & 1);
;             if (jn >= 0) SL_LWRITE(skA, svA, (sidx + 1) & 1);
	v_mfma_f32_16x16x32_bf16 v[52:55], v[56:59], v[68:71], v[52:55]
	v_add_f32_e32 v65, v78, v65
	v_add_f32_e32 v65, v79, v65
	v_pk_mul_f32 v[50:51], v[50:51], v[194:195] op_sel_hi:[1,0]
	s_waitcnt lgkmcnt(0)
	v_mfma_f32_16x16x32_bf16 v[72:75], v[60:63], v[84:87], v[52:55]
	v_mul_f32_e64 v48, v48, v194
	v_mul_f32_e64 v49, v49, v194
	v_pk_mul_f32 v[42:43], v[42:43], v[194:195] op_sel_hi:[1,0]
	v_pk_mul_f32 v[40:41], v[40:41], v[194:195] op_sel_hi:[1,0]
	ds_read_b128 v[52:55], v165 offset:12800
	v_mfma_f32_16x16x32_bf16 v[48:51], v[56:59], v[190:193], v[48:51]
	v_add_f32_e32 v56, v76, v65
	v_add_f32_e32 v65, v77, v56
	ds_read_b128 v[56:59], v165 offset:12864
	v_pk_mul_f32 v[46:47], v[46:47], v[64:65] op_sel_hi:[1,0]
	v_pk_mul_f32 v[44:45], v[44:45], v[64:65] op_sel_hi:[1,0]
	v_mfma_f32_16x16x32_bf16 v[60:63], v[60:63], v[228:231], v[48:51]
	v_mul_f32_e64 v38, v38, v64
	v_mul_f32_e64 v39, v39, v64
	v_pk_mul_f32 v[36:37], v[36:37], v[64:65] op_sel_hi:[1,0]
	v_pk_mul_f32 v[30:31], v[30:31], v[194:195] op_sel_hi:[1,0]
	s_waitcnt lgkmcnt(1)
	v_mfma_f32_16x16x32_bf16 v[44:47], v[52:55], v[68:71], v[44:47]
	v_add_f32_e32 v48, v188, v65
	v_add_f32_e32 v189, v189, v48
	ds_read_b128 v[48:51], v165 offset:15424
	s_waitcnt lgkmcnt(1)
	v_mfma_f32_16x16x32_bf16 v[76:79], v[56:59], v[84:87], v[44:47]
	v_mul_f32_e64 v28, v28, v194
	v_mul_f32_e64 v29, v29, v194
	v_fmac_f32_e32 v189, v187, v64
	v_pk_mul_f32 v[34:35], v[34:35], v[64:65] op_sel_hi:[1,0]
	ds_read_b128 v[44:47], v165 offset:15360
	v_mfma_f32_16x16x32_bf16 v[40:43], v[52:55], v[190:193], v[40:43]
	v_mul_f32_e64 v32, v32, v64
	v_mul_f32_e64 v33, v33, v64
	v_pk_mul_f32 v[26:27], v[26:27], v[194:195] op_sel_hi:[1,0]
	v_pk_mul_f32 v[24:25], v[24:25], v[194:195] op_sel_hi:[1,0]
	s_waitcnt lgkmcnt(0)
	v_mfma_f32_16x16x32_bf16 v[36:39], v[44:47], v[68:71], v[36:39]
	v_mov_b64_e32 v[52:53], v[72:73]
	v_mov_b32_e32 v187, v189
	v_mov_b32_e32 v163, v227
	v_mfma_f32_16x16x32_bf16 v[56:59], v[56:59], v[228:231], v[40:43]
	v_mov_b32_e32 v161, v232
	v_mov_b64_e32 v[54:55], v[74:75]
	s_nop 0
	v_add_f32_e32 v40, 0, v233
	v_add_f32_e32 v40, v195, v40
	v_add_f32_e32 v40, v234, v40
	v_mfma_f32_16x16x32_bf16 v[80:83], v[48:51], v[84:87], v[36:39]
	v_add_f32_e32 v40, v235, v40
	v_add_f32_e32 v40, v236, v40
	v_add_f32_e32 v40, v237, v40
	ds_read_b128 v[36:39], v226 offset:10240
	v_mfma_f32_16x16x32_bf16 v[28:31], v[44:47], v[190:193], v[28:31]
	v_add_f32_e32 v44, v238, v40
	ds_read_b128 v[40:43], v226 offset:10304
	v_mfma_f32_16x16x32_bf16 v[64:67], v[48:51], v[228:231], v[28:31]
	v_mov_b64_e32 v[48:49], v[60:61]
	v_mov_b64_e32 v[50:51], v[62:63]
	s_nop 2
	v_add_f32_e32 v28, v239, v44
	v_add_f32_e32 v28, v240, v28
	v_add_f32_e32 v44, v241, v28
	s_waitcnt lgkmcnt(1)
	v_mfma_f32_16x16x32_bf16 v[28:31], v[36:39], v[68:71], v[32:35]
	v_mfma_f32_16x16x32_bf16 v[24:27], v[36:39], v[190:193], v[24:27]
	s_nop 1
	v_add_f32_e32 v32, v242, v44
	v_add_f32_e32 v32, v243, v32
	v_add_f32_e32 v32, v244, v32
	s_waitcnt lgkmcnt(0)
	v_mfma_f32_16x16x32_bf16 v[84:87], v[40:43], v[84:87], v[28:31]
	v_mov_b64_e32 v[44:45], v[76:77]
	v_mov_b64_e32 v[36:37], v[80:81]
	v_mov_b64_e32 v[46:47], v[78:79]
	v_mfma_f32_16x16x32_bf16 v[68:71], v[40:43], v[228:231], v[24:27]
	v_add_f32_e32 v28, v245, v32
	v_add_f32_e32 v28, v246, v28
	v_add_f32_e32 v188, v247, v28
	v_fmac_f32_e32 v188, v186, v194
	v_mov_b64_e32 v[32:33], v[84:85]
	v_mov_b64_e32 v[40:41], v[56:57]
	v_mov_b64_e32 v[28:29], v[64:65]
	s_nop 0
	v_mov_b64_e32 v[24:25], v[68:69]
	v_mov_b32_e32 v186, v188
	v_mov_b64_e32 v[38:39], v[82:83]
	v_mov_b64_e32 v[34:35], v[86:87]
	v_mov_b64_e32 v[42:43], v[58:59]
	v_mov_b64_e32 v[30:31], v[66:67]
	v_mov_b64_e32 v[26:27], v[70:71]
	s_andn2_b64 vcc, exec, s[54:55]
	s_cbranch_vccnz .LBB0_1046
.LBB0_1045:
	s_andn2_b32 s10, 1, s43
	s_mulk_i32 s10, 0x5000
	s_add_i32 s10, s10, 0
	s_add_i32 s10, s10, 0x10800
	v_add3_u32 v165, s10, v221, v92
	s_waitcnt vmcnt(1)
	ds_write_b128 v165, v[16:19]
	v_add3_u32 v165, s10, v222, v92
	s_waitcnt vmcnt(0)
	ds_write_b128 v165, v[20:23] offset:10240

; #define LAS __attribute__((address_space(3)))
; __device__ __forceinline__ f32x4 mfma16(bf16x8 a, bf16x8 b, f32x4 c) { return __builtin_amdgcn_mfma_f32_16x16x32_bf16(a, b, c, 0, 0, 0); }
; template <int MODE>
; __device__ __forceinline__ void nsa_soft(f32x4 (&st)[4], const float (&Bl)[16], float cl, bool fast, int keybase, int t, bool sel, float& m2, float& l, f32x4 (&o)[4], float lfin, LAS float* imp, int lane) {
;     const int kg = lane >> 4;
; #pragma unroll
;     for (int tau = 0; tau < 4; ++tau)
; #pragma unroll
;         for (int r = 0; r < 4; ++r) st[tau][r] = __builtin_fmaf(st[tau][r], LOG2E, Bl[tau * 4 + r]);
;     if (!fast) {
; #pragma unroll
;         for (int tau = 0; tau < 4; ++tau)
; #pragma unroll
;             for (int r = 0; r < 4; ++r) { const int off = keybase + 32 * (tau >> 1) + 8 * kg + 4 * (tau & 1) + r;
;                 int dist; bool valid;
;                 if (MODE <= 1) { dist = t - (16 * off + 31); valid = dist >= 0; }
;                 else if (MODE == 2) { dist = t - off; valid = sel && dist >= 0; }
;                 else { dist = t - off; valid = dist >= 0 && dist < 512; }
;                 st[tau][r] = valid ? st[tau][r] : -INFINITY; }
;     }
; template <int MODE> ...
;     const int kg = lane >> 4;
;     f32x4 st[2][4];
;     { const int rho = lane & 15, dof = kg * 8;
; #pragma unroll
;       for (int tau = 0; tau < 4; ++tau) { const LAS bf16* rp = kt + (16 * tau + rho) * KT_LD + dof;
;           const bf16x8 k0 = *(const LAS bf16x8*)(rp), k1 = *(const LAS bf16x8*)(rp + 32);
; #pragma unroll
;           for (int s = 0; s < 2; ++s) { st[s][tau] = (f32x4){0.f, 0.f, 0.f, 0.f}; st[s][tau] = mfma16(k0, qf[s][0], st[s][tau]); st[s][tau] = mfma16(k1, qf[s][1], st[s][tau]); } } }
.LBB0_1057:
	s_bitcmp1_b32 s17, 0
	s_cselect_b32 s13, 0x5000, 0
	v_add_u32_e32 v170, s13, v215
	v_add_u32_e32 v192, v170, v204
	ds_read_b128 v[56:59], v192
	ds_read_b128 v[60:63], v192 offset:64
	ds_read_b128 v[68:71], v192 offset:2560
	v_add_u32_e32 v193, v170, v205
	ds_read_b128 v[236:239], v193
	ds_read_b128 v[240:243], v193 offset:64
	s_waitcnt lgkmcnt(4)
	v_mfma_f32_16x16x32_bf16 v[64:67], v[56:59], v[0:3], 0
	ds_read_b128 v[182:185], v192 offset:5120
	ds_read_b128 v[232:235], v192 offset:5184
	s_add_i32 s12, s12, 63
	v_mfma_f32_16x16x32_bf16 v[56:59], v[56:59], v[8:11], 0
	s_cmp_le_i32 s12, s4
	s_cselect_b64 s[12:13], -1, 0
	s_cmpk_lt_i32 s16, 0x200
	s_waitcnt lgkmcnt(5)
	v_mfma_f32_16x16x32_bf16 v[64:67], v[60:63], v[4:7], v[64:67]
	s_cselect_b64 s[18:19], -1, 0
	s_and_b64 s[12:13], s[12:13], s[18:19]
	v_add_u32_e32 v228, s16, v219
	v_mfma_f32_16x16x32_bf16 v[56:59], v[60:63], v[12:15], v[56:59]
	ds_read_b128 v[60:63], v192 offset:2624
	s_and_b64 vcc, exec, s[12:13]
	v_add_u32_e32 v231, -7, v228
	s_waitcnt lgkmcnt(5)
	v_mfma_f32_16x16x32_bf16 v[166:169], v[68:71], v[0:3], 0
	v_add_u32_e32 v230, -9, v228
	v_add_u32_e32 v229, -10, v228
	v_subrev_u32_e32 v226, 39, v228
	s_waitcnt lgkmcnt(0)
	v_mfma_f32_16x16x32_bf16 v[172:175], v[60:63], v[4:7], v[166:169]
	v_subrev_u32_e32 v227, 40, v228
	s_nop 1
	v_pk_fma_f32 v[168:169], v[64:65], s[22:23], v[72:73] op_sel_hi:[1,0,1]
	v_pk_fma_f32 v[166:167], v[66:67], s[22:23], v[74:75] op_sel_hi:[1,0,1]
	v_mfma_f32_16x16x32_bf16 v[68:71], v[68:71], v[8:11], 0
	s_nop 1
	v_fma_f32 v170, v174, s22, v78
	v_fma_f32 v171, v175, s22, v79
	v_pk_fma_f32 v[172:173], v[172:173], s[22:23], v[76:77] op_sel_hi:[1,0,1]
	v_subrev_u32_e32 v195, 41, v228
	v_mfma_f32_16x16x32_bf16 v[64:67], v[236:239], v[0:3], 0
	v_subrev_u32_e32 v194, 42, v228
	v_mfma_f32_16x16x32_bf16 v[60:63], v[60:63], v[12:15], v[68:71]
	v_mfma_f32_16x16x32_bf16 v[68:71], v[182:185], v[0:3], 0
	v_mfma_f32_16x16x32_bf16 v[64:67], v[240:243], v[4:7], v[64:67]
	v_mfma_f32_16x16x32_bf16 v[68:71], v[232:235], v[4:7], v[68:71]
	s_nop 6
	v_fma_f32 v180, v64, s22, v84
	v_fma_f32 v181, v65, s22, v85
	v_pk_fma_f32 v[178:179], v[66:67], s[22:23], v[86:87] op_sel_hi:[1,0,1]
	v_mfma_f32_16x16x32_bf16 v[64:67], v[182:185], v[8:11], 0
	v_fma_f32 v174, v68, s22, v80
	v_fma_f32 v175, v69, s22, v81
	v_pk_fma_f32 v[176:177], v[70:71], s[22:23], v[82:83] op_sel_hi:[1,0,1]
	v_mfma_f32_16x16x32_bf16 v[68:71], v[232:235], v[12:15], v[64:67]
	v_mfma_f32_16x16x32_bf16 v[64:67], v[236:239], v[8:11], 0
	v_mfma_f32_16x16x32_bf16 v[64:67], v[240:243], v[12:15], v[64:67]
	s_cbranch_vccnz .LBB0_1059
	v_add_u32_e32 v182, s20, v155
	v_cmp_gt_u32_e32 vcc, s78, v231
	v_add_u32_e32 v183, -12, v228
	v_add_u32_e32 v184, -13, v228
	v_cndmask_b32_e32 v168, v225, v168, vcc
	v_cmp_lt_u32_e32 vcc, s96, v182
	v_add_u32_e32 v182, -11, v228
	v_add_u32_e32 v185, -14, v228
	v_cndmask_b32_e32 v169, v225, v169, vcc
	v_cmp_gt_u32_e32 vcc, s78, v230
	s_nop 1
	v_cndmask_b32_e32 v166, v225, v166, vcc
	v_cmp_gt_u32_e32 vcc, s78, v229
	s_nop 1
	v_cndmask_b32_e32 v167, v225, v167, vcc
	v_cmp_gt_u32_e32 vcc, s78, v182
	v_subrev_u32_e32 v182, 43, v228
	s_nop 0
	v_cndmask_b32_e32 v172, v225, v172, vcc
	v_cmp_gt_u32_e32 vcc, s78, v183
	v_subrev_u32_e32 v183, 44, v228
	s_nop 0
	v_cndmask_b32_e32 v173, v225, v173, vcc
	v_cmp_gt_u32_e32 vcc, s78, v184
	v_subrev_u32_e32 v184, 45, v228
	s_nop 0
	v_cndmask_b32_e32 v170, v225, v170, vcc
	v_cmp_gt_u32_e32 vcc, s78, v185
	v_subrev_u32_e32 v185, 46, v228
	s_nop 0
	v_cndmask_b32_e32 v171, v225, v171, vcc
	v_cmp_gt_u32_e32 vcc, s78, v226
	s_nop 1
	v_cndmask_b32_e32 v174, v225, v174, vcc
	v_cmp_gt_u32_e32 vcc, s78, v227
	s_nop 1
	v_cndmask_b32_e32 v175, v225, v175, vcc
	v_cmp_gt_u32_e32 vcc, s78, v195
	s_nop 1
	v_cndmask_b32_e32 v176, v225, v176, vcc
	v_cmp_gt_u32_e32 vcc, s78, v194
	s_nop 1
	v_cndmask_b32_e32 v177, v225, v177, vcc
	v_cmp_gt_u32_e32 vcc, s78, v182
	s_nop 1
	v_cndmask_b32_e32 v180, v225, v180, vcc
	v_cmp_gt_u32_e32 vcc, s78, v183
	s_nop 1
	v_cndmask_b32_e32 v181, v225, v181, vcc
	v_cmp_gt_u32_e32 vcc, s78, v184
	s_nop 1
	v_cndmask_b32_e32 v178, v225, v178, vcc
	v_cmp_gt_u32_e32 vcc, s78, v185
	s_nop 1
	v_cndmask_b32_e32 v179, v225, v179, vcc

; #define LAS __attribute__((address_space(3)))
; __device__ __forceinline__ f32x4 mfma16(bf16x8 a, bf16x8 b, f32x4 c) { return __builtin_amdgcn_mfma_f32_16x16x32_bf16(a, b, c, 0, 0, 0); }
; template <int MODE>
; __device__ __forceinline__ void nsa_soft(f32x4 (&st)[4], const float (&Bl)[16], float cl, bool fast, int keybase, int t, bool sel, float& m2, float& l, f32x4 (&o)[4], float lfin, LAS float* imp, int lane) {
;     ...
;     } else {
;         float mloc = fmaxf(fmaxf(fmaxf(st[0][0], st[0][1]), fmaxf(st[0][2], st[0][3])), fmaxf(fmaxf(st[1][0], st[1][1]), fmaxf(st[1][2], st[1][3])));
;         mloc = fmaxf(mloc, fmaxf(fmaxf(fmaxf(st[2][0], st[2][1]), fmaxf(st[2][2], st[2][3])), fmaxf(fmaxf(st[3][0], st[3][1]), fmaxf(st[3][2], st[3][3]))));
;         mloc = xrow16_max(mloc);
;         const float mnew = fmaxf(m2, mloc + cl); const float alpha = __builtin_amdgcn_exp2f(m2 - mnew); m2 = mnew;
;         const float sh = cl - mnew;
;         float ps = 0.f;
; #pragma unroll
;         for (int tau = 0; tau < 4; ++tau)
; #pragma unroll
;             for (int r = 0; r < 4; ++r) { const float p = __builtin_amdgcn_exp2f(st[tau][r] + sh); st[tau][r] = p; ps += p; }
;         l = l * alpha + ps;
;         if (MODE != 0) {
; #pragma unroll
;             for (int dt = 0; dt < 4; ++dt) o[dt] = o[dt] * alpha;
;         }
; template <int MODE> ...
;     ...
;     if (MODE != 0) {
;         bf16x8 pb[2][2];
; #pragma unroll
;         for (int s = 0; s < 2; ++s) { pb[s][0] = pack_p(st[s][0], st[s][1]); pb[s][1] = pack_p(st[s][2], st[s][3]); }
; #pragma unroll
;         for (int dt = 0; dt < 4; ++dt) { const LAS bf16* vp = vt + (dt * 16 + (lane & 15)) * KT_LD + 8 * kg;
;             const bf16x8 v0 = *(const LAS bf16x8*)(vp), v1 = *(const LAS bf16x8*)(vp + 32);
; #pragma unroll
;             for (int s = 0; s < 2; ++s) { o[s][dt] = mfma16(v0, pb[s][0], o[s][dt]); o[s][dt] = mfma16(v1, pb[s][1], o[s][dt]); } }
;     }
.LBB0_1061:
	v_add_u32_e32 v68, s20, v186
	v_cvt_f32_i32_e32 v69, v68
	v_max_f32_e32 v68, v232, v232
	v_max_f32_e32 v70, v233, v233
	v_max_f32_e32 v68, v68, v70
	v_fmac_f32_e32 v68, v154, v69
	v_max_f32_e32 v70, v191, v191
	v_max_f32_e32 v68, v70, v68
	v_fma_f32 v194, v154, v69, -v68
	v_add_f32_e32 v70, v169, v194
	v_add_f32_e32 v169, v170, v194
	v_add_f32_e32 v170, v171, v194
	v_add_f32_e32 v171, v174, v194
	v_add_f32_e32 v174, v177, v194
	v_add_f32_e32 v177, v178, v194
	v_add_f32_e32 v178, v179, v194
	v_add_u32_e32 v179, s20, v161
	v_add_f32_e32 v69, v168, v194
	v_add_f32_e32 v71, v166, v194
	v_add_f32_e32 v166, v167, v194
	v_add_f32_e32 v167, v172, v194
	v_add_f32_e32 v168, v173, v194
	v_add_f32_e32 v172, v175, v194
	v_add_f32_e32 v173, v176, v194
	v_add_f32_e32 v175, v180, v194
	v_add_f32_e32 v176, v181, v194
	v_cvt_f32_i32_e32 v180, v179
	v_max_f32_e32 v179, v57, v57
	v_max_f32_e32 v181, v56, v56
	v_max_f32_e32 v179, v181, v179
	v_max_f32_e32 v181, v59, v59
	v_max_f32_e32 v194, v58, v58
	v_max_f32_e32 v181, v194, v181
	v_max_f32_e32 v194, v63, v63
	v_max_f32_e32 v195, v62, v62
	v_max_f32_e32 v194, v195, v194
	v_max_f32_e32 v195, v61, v61
	v_max_f32_e32 v226, v60, v60
	v_max_f32_e32 v195, v226, v195
	v_max_f32_e32 v226, v67, v67
	v_max_f32_e32 v227, v66, v66
	v_max_f32_e32 v226, v227, v226
	v_max3_f32 v226, v64, v65, v226
	v_max3_f32 v179, v182, v183, v179
	v_max3_f32 v181, v184, v185, v181
	v_max3_f32 v194, v194, v195, v226
	v_max3_f32 v179, v179, v181, v194
	v_mov_b32_e32 v181, v179
	s_nop 1
	v_permlane16_swap_b32_e32 v179, v181
	v_max_f32_e32 v181, v181, v181
	v_max_f32_e32 v179, v179, v179
	v_max_f32_e32 v179, v179, v181
	v_mov_b32_e32 v181, v179
	s_nop 1
	v_permlane32_swap_b32_e32 v179, v181
	v_max_f32_e32 v181, v181, v181
	v_max_f32_e32 v179, v179, v179
	v_max_f32_e32 v179, v179, v181
	v_fmac_f32_e32 v179, v154, v180
	v_max_f32_e32 v181, v190, v190
	v_max_f32_e32 v179, v181, v179
	v_fma_f32 v194, v154, v180, -v179
	v_add_f32_e32 v56, v56, v194
	v_add_f32_e32 v180, v182, v194
	v_exp_f32_e32 v182, v56
	v_add_f32_e32 v56, v57, v194
	v_exp_f32_e32 v57, v56
	v_add_f32_e32 v56, v184, v194
	v_add_f32_e32 v181, v183, v194
	v_exp_f32_e32 v183, v56
	v_add_f32_e32 v56, v185, v194
	v_exp_f32_e32 v184, v56
	v_add_f32_e32 v56, v58, v194
	v_exp_f32_e32 v185, v56
	v_add_f32_e32 v56, v59, v194
	v_exp_f32_e32 v59, v56
	v_add_f32_e32 v56, v62, v194
	v_exp_f32_e32 v62, v56
	v_add_f32_e32 v56, v63, v194
	v_exp_f32_e32 v63, v56
	v_add_f32_e32 v56, v60, v194
	v_exp_f32_e32 v60, v56
	v_add_f32_e32 v56, v61, v194
	v_exp_f32_e32 v61, v56
	v_add_f32_e32 v56, v64, v194
	v_exp_f32_e32 v64, v56
	v_add_f32_e32 v56, v65, v194
	v_exp_f32_e32 v65, v56
	v_add_f32_e32 v56, v66, v194
	v_exp_f32_e32 v66, v56
	v_add_f32_e32 v56, v67, v194
	v_exp_f32_e32 v69, v69
	v_exp_f32_e32 v70, v70
	v_exp_f32_e32 v71, v71
	v_exp_f32_e32 v166, v166
	v_exp_f32_e32 v167, v167
	v_exp_f32_e32 v168, v168
	v_exp_f32_e32 v169, v169
	v_exp_f32_e32 v170, v170
	v_exp_f32_e32 v171, v171
	v_exp_f32_e32 v172, v172
	v_exp_f32_e32 v173, v173
	v_exp_f32_e32 v174, v174
	v_exp_f32_e32 v175, v175
	v_exp_f32_e32 v176, v176
	v_exp_f32_e32 v177, v177
	v_exp_f32_e32 v178, v178
	v_exp_f32_e32 v180, v180
	v_exp_f32_e32 v181, v181
	v_exp_f32_e32 v67, v56
	v_cvt_pk_bf16_f32 v226, v69, v70
	v_cvt_pk_bf16_f32 v227, v71, v166
	v_cvt_pk_bf16_f32 v228, v167, v168
	v_cvt_pk_bf16_f32 v229, v169, v170
	v_cvt_pk_bf16_f32 v230, v171, v172
	v_cvt_pk_bf16_f32 v231, v173, v174
	v_cvt_pk_bf16_f32 v232, v175, v176
	v_cvt_pk_bf16_f32 v233, v177, v178
	v_cvt_pk_bf16_f32 v234, v180, v181
	v_cvt_pk_bf16_f32 v235, v182, v57
	v_cvt_pk_bf16_f32 v236, v183, v184
	v_cvt_pk_bf16_f32 v237, v185, v59
	v_cvt_pk_bf16_f32 v238, v62, v63
	v_cvt_pk_bf16_f32 v239, v60, v61
	v_cvt_pk_bf16_f32 v240, v64, v65
	v_cvt_pk_bf16_f32 v241, v66, v67
	ds_read_b128 v[242:245], v192 offset:10240
	ds_read_b128 v[246:249], v192 offset:10304
	v_sub_f32_e32 v56, v191, v68
	v_sub_f32_e32 v58, v190, v179
	v_exp_f32_e32 v56, v56
	v_exp_f32_e32 v58, v58
	s_add_i32 s17, s17, 1
	s_andn2_b64 vcc, exec, s[10:11]
	v_pk_mul_f32 v[46:47], v[46:47], v[56:57] op_sel_hi:[1,0]
	v_pk_mul_f32 v[44:45], v[44:45], v[56:57] op_sel_hi:[1,0]
	v_pk_mul_f32 v[30:31], v[30:31], v[58:59] op_sel_hi:[1,0]
	v_pk_mul_f32 v[28:29], v[28:29], v[58:59] op_sel_hi:[1,0]
	s_waitcnt lgkmcnt(1)
	v_mfma_f32_16x16x32_bf16 v[44:47], v[242:245], v[226:229], v[44:47]
	v_mul_f32_e64 v42, v42, v56
	v_mul_f32_e64 v43, v43, v56
	v_pk_mul_f32 v[40:41], v[40:41], v[56:57] op_sel_hi:[1,0]
	v_pk_mul_f32 v[26:27], v[26:27], v[58:59] op_sel_hi:[1,0]
	v_mfma_f32_16x16x32_bf16 v[28:31], v[242:245], v[234:237], v[28:31]
	ds_read_b128 v[242:245], v192 offset:12800
	v_pk_mul_f32 v[24:25], v[24:25], v[58:59] op_sel_hi:[1,0]
	v_pk_mul_f32 v[38:39], v[38:39], v[56:57] op_sel_hi:[1,0]
	s_waitcnt lgkmcnt(1)
	v_mfma_f32_16x16x32_bf16 v[44:47], v[246:249], v[230:233], v[44:47]
	v_mul_f32_e64 v36, v36, v56
	v_mul_f32_e64 v37, v37, v56
	v_pk_mul_f32 v[22:23], v[22:23], v[58:59] op_sel_hi:[1,0]
	v_pk_mul_f32 v[20:21], v[20:21], v[58:59] op_sel_hi:[1,0]
	v_mfma_f32_16x16x32_bf16 v[28:31], v[246:249], v[238:241], v[28:31]
	ds_read_b128 v[246:249], v192 offset:12864
	v_pk_mul_f32 v[34:35], v[34:35], v[56:57] op_sel_hi:[1,0]
	v_pk_mul_f32 v[32:33], v[32:33], v[56:57] op_sel_hi:[1,0]
	s_waitcnt lgkmcnt(1)
	v_mfma_f32_16x16x32_bf16 v[40:43], v[242:245], v[226:229], v[40:43]
	v_mul_f32_e64 v18, v18, v58
	v_mul_f32_e64 v19, v19, v58
	v_pk_mul_f32 v[16:17], v[16:17], v[58:59] op_sel_hi:[1,0]
	v_mfma_f32_16x16x32_bf16 v[24:27], v[242:245], v[234:237], v[24:27]
	ds_read_b128 v[242:245], v192 offset:15360
	s_waitcnt lgkmcnt(1)
	v_mfma_f32_16x16x32_bf16 v[40:43], v[246:249], v[230:233], v[40:43]
	v_mfma_f32_16x16x32_bf16 v[24:27], v[246:249], v[238:241], v[24:27]
	ds_read_b128 v[246:249], v192 offset:15424
	s_waitcnt lgkmcnt(1)
	v_mfma_f32_16x16x32_bf16 v[36:39], v[242:245], v[226:229], v[36:39]
	v_mfma_f32_16x16x32_bf16 v[20:23], v[242:245], v[234:237], v[20:23]
	ds_read_b128 v[242:245], v193 offset:10240
	ds_read_b128 v[190:193], v193 offset:10304
	s_waitcnt lgkmcnt(1)
	v_mfma_f32_16x16x32_bf16 v[32:35], v[242:245], v[226:229], v[32:35]
	v_mfma_f32_16x16x32_bf16 v[16:19], v[242:245], v[234:237], v[16:19]
	v_mfma_f32_16x16x32_bf16 v[36:39], v[246:249], v[230:233], v[36:39]
	v_mfma_f32_16x16x32_bf16 v[20:23], v[246:249], v[238:241], v[20:23]
	s_waitcnt lgkmcnt(0)
	v_mfma_f32_16x16x32_bf16 v[32:35], v[190:193], v[230:233], v[32:35]
	v_mfma_f32_16x16x32_bf16 v[16:19], v[190:193], v[238:241], v[16:19]
	s_cbranch_vccnz .LBB0_1063
	s_bitcmp1_b32 s17, 0
	s_cselect_b32 s10, 0x5000, 0
	s_add_i32 s10, s10, 0
	s_add_i32 s10, s10, 0x10800
	v_add3_u32 v191, s10, v201, v92
	v_add3_u32 v190, s10, v206, v92
	s_waitcnt vmcnt(1)
	ds_write_b128 v191, v[48:51]
	s_waitcnt vmcnt(0)
	ds_write_b128 v190, v[52:55] offset:10240
